# hand-written load-pipelined sample attention unit in P2 (rolling window of K/V loads instead of load-wait-mfma per step)
# speedup vs baseline: 1.0060x; 1.0060x over previous
.LBB0_1114:
	s_mov_b64 s[68:69], 0
	s_and_b64 vcc, exec, s[0:1]
	s_mov_b64 s[0:1], 0
	s_cbranch_vccz .LBB0_1243
	s_add_i32 s34, s63, 0xfffffde0
	s_lshr_b32 s70, s34, 3
	s_and_b32 s71, s34, 7
	v_lshrrev_b32_e32 v76, 6, v0
	v_and_b32_e32 v77, 15, v0
	v_bfe_u32 v75, v0, 4, 2
	v_readfirstlane_b32 s72, v76
	v_readlane_b32 s34, v254, 33
	v_readlane_b32 s35, v254, 34
	v_readlane_b32 s36, v254, 35
	v_readlane_b32 s37, v254, 36
	v_lshlrev_b32_e32 v72, 11, v77
	v_lshl_add_u32 v72, v75, 5, v72
	v_lshlrev_b32_e32 v73, 13, v75
	v_lshl_add_u32 v73, v77, 2, v73
	v_lshlrev_b32_e32 v74, 10, v77
	v_lshl_add_u32 v74, v75, 4, v74
	s_lshl_b32 s38, s70, 22
	s_lshl_b32 s39, s71, 8
	s_add_i32 s38, s38, s39
	s_lshl_b32 s39, s72, 15
	s_add_i32 s38, s38, s39
	s_add_u32 s74, s34, s38
	s_addc_u32 s75, s35, 0
	s_add_u32 s76, s36, s38
	s_addc_u32 s77, s37, 0
	s_add_u32 s76, s76, 0x1000
	s_addc_u32 s77, s77, 0
	s_add_u32 s78, s76, 0x40000
	s_addc_u32 s79, s77, 0
	s_lshl_b32 s38, s70, 14
	s_lshl_b32 s39, s71, 7
	s_add_i32 s38, s38, s39
	s_add_i32 s39, s38, 0x7faea00
	s_add_u32 s80, s90, s39
	s_addc_u32 s81, s91, 0
	s_add_i32 s39, s38, 0x1e2ea00
	s_add_u32 s86, s90, s39
	s_addc_u32 s87, s91, 0
	s_lshl_b32 s38, s70, 15
	s_lshl_b32 s39, s71, 8
	s_add_i32 s38, s38, s39
	s_add_i32 s39, s38, 0x821c000
	s_add_u32 s82, s88, s39
	s_addc_u32 s83, s89, 0
	s_add_i32 s39, s38, 0x829d000
	s_add_u32 s84, s88, s39
	s_addc_u32 s85, s89, 0
	global_load_dwordx4 v[64:67], v74, s[80:81]
	global_load_dwordx4 v[68:71], v74, s[80:81] offset:64
	s_cmp_lg_u32 s72, 0
	s_cbranch_scc1 .Lsa_pre_nz
	global_load_dwordx4 v[232:235], v72, s[82:83]
	global_load_dwordx4 v[236:239], v72, s[82:83] offset:16
	global_load_dwordx4 v[240:243], v72, s[82:83] offset:128
	global_load_dwordx4 v[244:247], v72, s[82:83] offset:144
.Lsa_pre_nz:
	global_load_dwordx4 v[16:19], v72, s[74:75]
	global_load_dwordx4 v[20:23], v72, s[74:75] offset:16
	global_load_dwordx4 v[24:27], v72, s[74:75] offset:128
	global_load_dwordx4 v[28:31], v72, s[74:75] offset:144
	s_add_u32 s74, s74, 0x40000
	s_addc_u32 s75, s75, 0
	global_load_dwordx4 v[32:35], v72, s[74:75]
	global_load_dwordx4 v[36:39], v72, s[74:75] offset:16
	global_load_dwordx4 v[40:43], v72, s[74:75] offset:128
	global_load_dwordx4 v[44:47], v72, s[74:75] offset:144
	s_add_u32 s74, s74, 0x40000
	s_addc_u32 s75, s75, 0
	global_load_dwordx4 v[48:51], v72, s[74:75]
	global_load_dwordx4 v[52:55], v72, s[74:75] offset:16
	global_load_dwordx4 v[56:59], v72, s[74:75] offset:128
	global_load_dwordx4 v[60:63], v72, s[74:75] offset:144
	s_add_u32 s74, s74, 0x40000
	s_addc_u32 s75, s75, 0
	global_load_dwordx4 v[180:183], v72, s[74:75]
	global_load_dwordx4 v[184:187], v72, s[74:75] offset:16
	global_load_dwordx4 v[188:191], v72, s[74:75] offset:128
	global_load_dwordx4 v[192:195], v72, s[74:75] offset:144
	s_add_u32 s74, s74, 0x40000
	s_addc_u32 s75, s75, 0
	global_load_dwordx4 v[200:203], v72, s[74:75]
	global_load_dwordx4 v[204:207], v72, s[74:75] offset:16
	global_load_dwordx4 v[208:211], v72, s[74:75] offset:128
	global_load_dwordx4 v[212:215], v72, s[74:75] offset:144
	s_add_u32 s74, s74, 0x40000
	s_addc_u32 s75, s75, 0
	global_load_dwordx4 v[216:219], v72, s[74:75]
	global_load_dwordx4 v[220:223], v72, s[74:75] offset:16
	global_load_dwordx4 v[224:227], v72, s[74:75] offset:128
	global_load_dwordx4 v[228:231], v72, s[74:75] offset:144
	s_add_u32 s74, s74, 0x40000
	s_addc_u32 s75, s75, 0
	s_add_i32 s0, s63, 0xfffffde0
	s_lshr_b32 s60, s0, 3
	s_lshl_b32 s92, s60, 14
	v_readlane_b32 s12, v254, 29
	s_and_b32 s10, s63, 7
	s_lshl_b64 s[0:1], s[92:93], 2
	v_readlane_b32 s20, v254, 37
	v_mov_b32_e32 v105, v0
	v_readlane_b32 s21, v254, 38
	s_add_u32 s0, s20, s0
	s_addc_u32 s1, s21, s1
	s_lshl_b32 s2, s10, 2
	v_lshlrev_b32_e32 v2, 2, v105
	s_add_u32 s0, s0, s2
	v_ashrrev_i32_e32 v3, 31, v2
	s_addc_u32 s1, s1, 0
	v_lshlrev_b64 v[4:5], 5, v[2:3]
	v_lshl_add_u64 v[4:5], s[0:1], 0, v[4:5]
	global_load_dword v6, v[4:5], off
	v_or_b32_e32 v4, 1, v2
	v_ashrrev_i32_e32 v5, 31, v4
	v_lshlrev_b64 v[4:5], 5, v[4:5]
	v_lshl_add_u64 v[4:5], s[0:1], 0, v[4:5]
	global_load_dword v7, v[4:5], off
	v_or_b32_e32 v4, 2, v2
	v_ashrrev_i32_e32 v5, 31, v4
	v_or_b32_e32 v2, 3, v2
	v_lshlrev_b64 v[4:5], 5, v[4:5]
	v_ashrrev_i32_e32 v3, 31, v2
	v_lshl_add_u64 v[4:5], s[0:1], 0, v[4:5]
	v_lshlrev_b64 v[2:3], 5, v[2:3]
	global_load_dword v8, v[4:5], off
	v_lshl_add_u64 v[2:3], s[0:1], 0, v[2:3]
	global_load_dword v3, v[2:3], off
	v_cmp_lt_i32_e32 vcc, v87, v84
	v_cmp_lt_i32_e64 s[0:1], v88, v84
	v_and_b32_e32 v106, 63, v105
	v_cndmask_b32_e32 v2, v87, v83, vcc
	v_lshlrev_b32_e32 v9, 2, v2
	v_cmp_eq_u32_e32 vcc, 0, v106
	v_cmp_gt_u32_e64 s[28:29], 16, v106
	v_ashrrev_i32_e32 v107, 6, v105
	v_readlane_b32 s13, v254, 30
	v_readlane_b32 s14, v254, 31
	v_readlane_b32 s15, v254, 32
	v_readlane_b32 s16, v254, 33
	v_readlane_b32 s17, v254, 34
	v_readlane_b32 s18, v254, 35
	v_readlane_b32 s19, v254, 36
	v_readlane_b32 s22, v254, 39
	v_readlane_b32 s23, v254, 40
	v_readlane_b32 s24, v254, 41
	v_readlane_b32 s25, v254, 42
	v_readlane_b32 s26, v254, 43
	v_readlane_b32 s27, v254, 44
	s_waitcnt vmcnt(3)
	v_add_f32_e32 v4, 0, v6
	s_waitcnt vmcnt(2)
	v_add_f32_e32 v5, v4, v7
	v_cndmask_b32_e64 v7, v88, v83, s[0:1]
	v_lshlrev_b32_e32 v7, 2, v7
	s_waitcnt vmcnt(1)
	v_add_f32_e32 v2, v5, v8
	s_waitcnt vmcnt(0)
	v_add_f32_e32 v3, v2, v3
	ds_bpermute_b32 v6, v9, v3
	s_waitcnt lgkmcnt(0)
	v_add_f32_e32 v6, v3, v6
	v_cndmask_b32_e32 v6, v6, v3, vcc
	ds_bpermute_b32 v7, v7, v6
	v_cmp_lt_i32_e32 vcc, v89, v84
	s_waitcnt lgkmcnt(0)
	v_add_f32_e32 v7, v6, v7
	v_cndmask_b32_e32 v8, v89, v83, vcc
	v_cmp_gt_u32_e32 vcc, 2, v106
	v_lshlrev_b32_e32 v8, 2, v8
	s_nop 0
	v_cndmask_b32_e32 v6, v7, v6, vcc
	ds_bpermute_b32 v7, v8, v6
	v_cmp_lt_i32_e32 vcc, v90, v84
	s_waitcnt lgkmcnt(0)
	v_add_f32_e32 v7, v6, v7
	v_cndmask_b32_e32 v8, v90, v83, vcc
	v_cmp_gt_u32_e32 vcc, 4, v106
	v_lshlrev_b32_e32 v8, 2, v8
	s_nop 0
	v_cndmask_b32_e32 v6, v7, v6, vcc
	ds_bpermute_b32 v7, v8, v6
	v_cmp_lt_i32_e32 vcc, v91, v84
	s_waitcnt lgkmcnt(0)
	v_add_f32_e32 v7, v6, v7
	v_cndmask_b32_e32 v8, v91, v83, vcc
	v_cmp_gt_u32_e32 vcc, 8, v106
	v_lshlrev_b32_e32 v8, 2, v8
	s_nop 0
	v_cndmask_b32_e32 v6, v7, v6, vcc
	ds_bpermute_b32 v7, v8, v6
	v_cmp_lt_i32_e32 vcc, v92, v84
	s_waitcnt lgkmcnt(0)
	v_add_f32_e32 v7, v6, v7
	v_cndmask_b32_e32 v8, v92, v83, vcc
	v_lshlrev_b32_e32 v8, 2, v8
	v_cndmask_b32_e64 v6, v7, v6, s[28:29]
	ds_bpermute_b32 v7, v8, v6
	v_cmp_eq_u32_e32 vcc, 63, v106
	s_waitcnt lgkmcnt(0)
	v_add_f32_e32 v7, v6, v7
	s_and_saveexec_b64 s[0:1], vcc
	v_lshl_add_u32 v8, v107, 2, 16
	ds_write_b32 v8, v7 offset:8448
	s_or_b64 exec, exec, s[0:1]
	v_cmp_gt_u32_e32 vcc, 32, v106
	s_waitcnt lgkmcnt(0)
	s_barrier
	v_cndmask_b32_e32 v6, v7, v6, vcc
	v_sub_f32_e32 v6, v6, v3
	v_cmp_lt_i32_e32 vcc, 0, v107
	s_and_saveexec_b64 s[0:1], vcc
	s_cbranch_execz .LBB0_1127
	v_add_u32_e32 v7, -1, v107
	v_cmp_lt_u32_e32 vcc, 6, v7
	v_mov_b32_e32 v7, 0
	s_and_saveexec_b64 s[2:3], vcc
	s_cbranch_execz .LBB0_1122
	v_and_b32_e32 v7, 0x7ffffff8, v107
	s_mov_b32 s4, 0
	s_mov_b64 s[6:7], 0
	v_readlane_b32 s5, v255, 0

.LBB0_1127:
	s_or_b64 exec, exec, s[0:1]
	v_pk_add_f32 v[4:5], v[4:5], v[6:7] op_sel_hi:[1,0]
	v_pk_add_f32 v[2:3], v[2:3], v[6:7] op_sel_hi:[1,0]
	s_lshl_b32 s4, s60, 7
	v_lshl_add_u32 v8, v105, 4, 16
	v_pk_mul_f32 v[4:5], v[4:5], s[62:63] op_sel_hi:[1,0]
	v_pk_mul_f32 v[6:7], v[2:3], s[62:63] op_sel_hi:[1,0]
	v_cmp_eq_u32_e32 vcc, s30, v105
	ds_write_b128 v8, v[4:7]
	s_and_saveexec_b64 s[0:1], vcc
	s_cbranch_execz .LBB0_1129
	s_or_b32 s2, s4, s10
	s_mov_b32 s3, s93
	s_lshl_b64 s[2:3], s[2:3], 2
	s_add_u32 s2, s88, s2
	s_addc_u32 s3, s89, s3
	global_load_dword v112, v82, s[2:3]
	global_load_dword v113, v82, s[2:3] offset:32
	global_load_dword v114, v82, s[2:3] offset:64
	global_load_dword v115, v82, s[2:3] offset:96
	global_load_dword v116, v82, s[2:3] offset:128
	global_load_dword v117, v82, s[2:3] offset:160
	global_load_dword v118, v82, s[2:3] offset:192
	global_load_dword v119, v82, s[2:3] offset:224
	global_load_dword v120, v82, s[2:3] offset:256
	global_load_dword v121, v82, s[2:3] offset:288
	global_load_dword v122, v82, s[2:3] offset:320
	global_load_dword v123, v82, s[2:3] offset:352
	global_load_dword v124, v82, s[2:3] offset:384
	global_load_dword v125, v82, s[2:3] offset:416
	global_load_dword v126, v82, s[2:3] offset:448
	global_load_dword v127, v82, s[2:3] offset:480
	s_waitcnt vmcnt(0)
	v_add_f32_e32 v112, v3, v112
	v_add_f32_e32 v113, v112, v113
	v_add_f32_e32 v114, v113, v114
	v_add_f32_e32 v115, v114, v115
	v_add_f32_e32 v116, v115, v116
	v_add_f32_e32 v117, v116, v117
	v_add_f32_e32 v118, v117, v118
	v_add_f32_e32 v119, v118, v119
	v_add_f32_e32 v120, v119, v120
	v_add_f32_e32 v121, v120, v121
	v_add_f32_e32 v122, v121, v122
	v_add_f32_e32 v123, v122, v123
	v_add_f32_e32 v124, v123, v124
	v_add_f32_e32 v125, v124, v125
	v_add_f32_e32 v126, v125, v126
	v_add_f32_e32 v127, v126, v127
	v_pk_mul_f32 v[112:113], v[112:113], s[62:63] op_sel_hi:[1,0]
	v_pk_mul_f32 v[114:115], v[114:115], s[62:63] op_sel_hi:[1,0]
	v_pk_mul_f32 v[116:117], v[116:117], s[62:63] op_sel_hi:[1,0]
	v_pk_mul_f32 v[118:119], v[118:119], s[62:63] op_sel_hi:[1,0]
	v_pk_mul_f32 v[120:121], v[120:121], s[62:63] op_sel_hi:[1,0]
	v_pk_mul_f32 v[122:123], v[122:123], s[62:63] op_sel_hi:[1,0]
	v_pk_mul_f32 v[124:125], v[124:125], s[62:63] op_sel_hi:[1,0]
	v_pk_mul_f32 v[126:127], v[126:127], s[62:63] op_sel_hi:[1,0]
	ds_write_b128 v100, v[112:115] offset:8192
	ds_write_b128 v100, v[116:119] offset:8208
	ds_write_b128 v100, v[120:123] offset:8224
	ds_write_b128 v100, v[124:127] offset:8240
.LBB0_1129:
	s_or_b64 exec, exec, s[0:1]
	s_waitcnt lgkmcnt(0)
	s_barrier
	v_lshlrev_b32_e32 v80, 4, v75
	s_lshl_b32 s0, s72, 6
	s_add_i32 s0, s0, 16
	v_add_u32_e32 v80, s0, v80
	v_lshlrev_b32_e32 v81, 2, v0
	v_mov_b32_e32 v176, v101
	v_mov_b32_e32 v177, v101
	v_mov_b32_e32 v178, v101
	v_mov_b32_e32 v179, v101
	s_waitcnt vmcnt(20)
	ds_read_b128 v[112:115], v80 offset:0
	v_cvt_pk_bf16_f32 v2, v16, v17
	v_cvt_pk_bf16_f32 v3, v18, v19
	v_cvt_pk_bf16_f32 v4, v20, v21
	v_cvt_pk_bf16_f32 v5, v22, v23
	v_cvt_pk_bf16_f32 v6, v24, v25
	v_cvt_pk_bf16_f32 v7, v26, v27
	v_cvt_pk_bf16_f32 v8, v28, v29
	v_cvt_pk_bf16_f32 v9, v30, v31
	global_load_dwordx4 v[16:19], v72, s[74:75]
	global_load_dwordx4 v[20:23], v72, s[74:75] offset:16
	global_load_dwordx4 v[24:27], v72, s[74:75] offset:128
	global_load_dwordx4 v[28:31], v72, s[74:75] offset:144
	s_add_u32 s74, s74, 0x40000
	s_addc_u32 s75, s75, 0
	s_waitcnt lgkmcnt(0)
	v_mfma_f32_16x16x32_bf16 v[112:115], v[2:5], v[64:67], v[112:115]
	v_mfma_f32_16x16x32_bf16 v[112:115], v[6:9], v[68:71], v[112:115]
	s_waitcnt vmcnt(20)
	ds_read_b128 v[116:119], v80 offset:512
	v_cvt_pk_bf16_f32 v2, v32, v33
	v_cvt_pk_bf16_f32 v3, v34, v35
	v_cvt_pk_bf16_f32 v4, v36, v37
	v_cvt_pk_bf16_f32 v5, v38, v39
	v_cvt_pk_bf16_f32 v6, v40, v41
	v_cvt_pk_bf16_f32 v7, v42, v43
	v_cvt_pk_bf16_f32 v8, v44, v45
	v_cvt_pk_bf16_f32 v9, v46, v47
	global_load_dwordx4 v[32:35], v72, s[74:75]
	global_load_dwordx4 v[36:39], v72, s[74:75] offset:16
	global_load_dwordx4 v[40:43], v72, s[74:75] offset:128
	global_load_dwordx4 v[44:47], v72, s[74:75] offset:144
	s_add_u32 s74, s74, 0x40000
	s_addc_u32 s75, s75, 0
	s_waitcnt lgkmcnt(0)
	v_mfma_f32_16x16x32_bf16 v[116:119], v[2:5], v[64:67], v[116:119]
	v_mfma_f32_16x16x32_bf16 v[116:119], v[6:9], v[68:71], v[116:119]
	s_waitcnt vmcnt(20)
	ds_read_b128 v[120:123], v80 offset:1024
	v_cvt_pk_bf16_f32 v2, v48, v49
	v_cvt_pk_bf16_f32 v3, v50, v51
	v_cvt_pk_bf16_f32 v4, v52, v53
	v_cvt_pk_bf16_f32 v5, v54, v55
	v_cvt_pk_bf16_f32 v6, v56, v57
	v_cvt_pk_bf16_f32 v7, v58, v59
	v_cvt_pk_bf16_f32 v8, v60, v61
	v_cvt_pk_bf16_f32 v9, v62, v63
	global_load_dwordx4 v[48:51], v72, s[74:75]
	global_load_dwordx4 v[52:55], v72, s[74:75] offset:16
	global_load_dwordx4 v[56:59], v72, s[74:75] offset:128
	global_load_dwordx4 v[60:63], v72, s[74:75] offset:144
	s_add_u32 s74, s74, 0x40000
	s_addc_u32 s75, s75, 0
	s_waitcnt lgkmcnt(0)
	v_mfma_f32_16x16x32_bf16 v[120:123], v[2:5], v[64:67], v[120:123]
	v_mfma_f32_16x16x32_bf16 v[120:123], v[6:9], v[68:71], v[120:123]
	s_waitcnt vmcnt(20)
	ds_read_b128 v[124:127], v80 offset:1536
	v_cvt_pk_bf16_f32 v2, v180, v181
	v_cvt_pk_bf16_f32 v3, v182, v183
	v_cvt_pk_bf16_f32 v4, v184, v185
	v_cvt_pk_bf16_f32 v5, v186, v187
	v_cvt_pk_bf16_f32 v6, v188, v189
	v_cvt_pk_bf16_f32 v7, v190, v191
	v_cvt_pk_bf16_f32 v8, v192, v193
	v_cvt_pk_bf16_f32 v9, v194, v195
	global_load_dwordx4 v[180:183], v72, s[74:75]
	global_load_dwordx4 v[184:187], v72, s[74:75] offset:16
	global_load_dwordx4 v[188:191], v72, s[74:75] offset:128
	global_load_dwordx4 v[192:195], v72, s[74:75] offset:144
	s_add_u32 s74, s74, 0x40000
	s_addc_u32 s75, s75, 0
	s_waitcnt lgkmcnt(0)
	v_mfma_f32_16x16x32_bf16 v[124:127], v[2:5], v[64:67], v[124:127]
	v_mfma_f32_16x16x32_bf16 v[124:127], v[6:9], v[68:71], v[124:127]
	s_waitcnt vmcnt(20)
	ds_read_b128 v[128:131], v80 offset:2048
	v_cvt_pk_bf16_f32 v2, v200, v201
	v_cvt_pk_bf16_f32 v3, v202, v203
	v_cvt_pk_bf16_f32 v4, v204, v205
	v_cvt_pk_bf16_f32 v5, v206, v207
	v_cvt_pk_bf16_f32 v6, v208, v209
	v_cvt_pk_bf16_f32 v7, v210, v211
	v_cvt_pk_bf16_f32 v8, v212, v213
	v_cvt_pk_bf16_f32 v9, v214, v215
	global_load_dwordx4 v[200:203], v72, s[74:75]
	global_load_dwordx4 v[204:207], v72, s[74:75] offset:16
	global_load_dwordx4 v[208:211], v72, s[74:75] offset:128
	global_load_dwordx4 v[212:215], v72, s[74:75] offset:144
	s_add_u32 s74, s74, 0x40000
	s_addc_u32 s75, s75, 0
	s_waitcnt lgkmcnt(0)
	v_mfma_f32_16x16x32_bf16 v[128:131], v[2:5], v[64:67], v[128:131]
	v_mfma_f32_16x16x32_bf16 v[128:131], v[6:9], v[68:71], v[128:131]
	s_waitcnt vmcnt(20)
	ds_read_b128 v[132:135], v80 offset:2560
	v_cvt_pk_bf16_f32 v2, v216, v217
	v_cvt_pk_bf16_f32 v3, v218, v219
	v_cvt_pk_bf16_f32 v4, v220, v221
	v_cvt_pk_bf16_f32 v5, v222, v223
	v_cvt_pk_bf16_f32 v6, v224, v225
	v_cvt_pk_bf16_f32 v7, v226, v227
	v_cvt_pk_bf16_f32 v8, v228, v229
	v_cvt_pk_bf16_f32 v9, v230, v231
	global_load_dwordx4 v[216:219], v72, s[74:75]
	global_load_dwordx4 v[220:223], v72, s[74:75] offset:16
	global_load_dwordx4 v[224:227], v72, s[74:75] offset:128
	global_load_dwordx4 v[228:231], v72, s[74:75] offset:144
	s_add_u32 s74, s74, 0x40000
	s_addc_u32 s75, s75, 0
	s_waitcnt lgkmcnt(0)
	v_mfma_f32_16x16x32_bf16 v[132:135], v[2:5], v[64:67], v[132:135]
	v_mfma_f32_16x16x32_bf16 v[132:135], v[6:9], v[68:71], v[132:135]
	s_waitcnt vmcnt(20)
	ds_read_b128 v[136:139], v80 offset:3072
	v_cvt_pk_bf16_f32 v2, v16, v17
	v_cvt_pk_bf16_f32 v3, v18, v19
	v_cvt_pk_bf16_f32 v4, v20, v21
	v_cvt_pk_bf16_f32 v5, v22, v23
	v_cvt_pk_bf16_f32 v6, v24, v25
	v_cvt_pk_bf16_f32 v7, v26, v27
	v_cvt_pk_bf16_f32 v8, v28, v29
	v_cvt_pk_bf16_f32 v9, v30, v31
	global_load_dwordx4 v[16:19], v72, s[74:75]
	global_load_dwordx4 v[20:23], v72, s[74:75] offset:16
	global_load_dwordx4 v[24:27], v72, s[74:75] offset:128
	global_load_dwordx4 v[28:31], v72, s[74:75] offset:144
	s_add_u32 s74, s74, 0x40000
	s_addc_u32 s75, s75, 0
	s_waitcnt lgkmcnt(0)
	v_mfma_f32_16x16x32_bf16 v[136:139], v[2:5], v[64:67], v[136:139]
	v_mfma_f32_16x16x32_bf16 v[136:139], v[6:9], v[68:71], v[136:139]
	s_waitcnt vmcnt(20)
	ds_read_b128 v[140:143], v80 offset:3584
	v_cvt_pk_bf16_f32 v2, v32, v33
	v_cvt_pk_bf16_f32 v3, v34, v35
	v_cvt_pk_bf16_f32 v4, v36, v37
	v_cvt_pk_bf16_f32 v5, v38, v39
	v_cvt_pk_bf16_f32 v6, v40, v41
	v_cvt_pk_bf16_f32 v7, v42, v43
	v_cvt_pk_bf16_f32 v8, v44, v45
	v_cvt_pk_bf16_f32 v9, v46, v47
	global_load_dwordx4 v[32:35], v72, s[74:75]
	global_load_dwordx4 v[36:39], v72, s[74:75] offset:16
	global_load_dwordx4 v[40:43], v72, s[74:75] offset:128
	global_load_dwordx4 v[44:47], v72, s[74:75] offset:144
	s_add_u32 s74, s74, 0x40000
	s_addc_u32 s75, s75, 0
	s_waitcnt lgkmcnt(0)
	v_mfma_f32_16x16x32_bf16 v[140:143], v[2:5], v[64:67], v[140:143]
	v_mfma_f32_16x16x32_bf16 v[140:143], v[6:9], v[68:71], v[140:143]
	s_waitcnt vmcnt(20)
	ds_read_b128 v[144:147], v80 offset:4096
	v_cvt_pk_bf16_f32 v2, v48, v49
	v_cvt_pk_bf16_f32 v3, v50, v51
	v_cvt_pk_bf16_f32 v4, v52, v53
	v_cvt_pk_bf16_f32 v5, v54, v55
	v_cvt_pk_bf16_f32 v6, v56, v57
	v_cvt_pk_bf16_f32 v7, v58, v59
	v_cvt_pk_bf16_f32 v8, v60, v61
	v_cvt_pk_bf16_f32 v9, v62, v63
	global_load_dwordx4 v[48:51], v72, s[74:75]
	global_load_dwordx4 v[52:55], v72, s[74:75] offset:16
	global_load_dwordx4 v[56:59], v72, s[74:75] offset:128
	global_load_dwordx4 v[60:63], v72, s[74:75] offset:144
	s_add_u32 s74, s74, 0x40000
	s_addc_u32 s75, s75, 0
	s_waitcnt lgkmcnt(0)
	v_mfma_f32_16x16x32_bf16 v[144:147], v[2:5], v[64:67], v[144:147]
	v_mfma_f32_16x16x32_bf16 v[144:147], v[6:9], v[68:71], v[144:147]
	s_waitcnt vmcnt(20)
	ds_read_b128 v[148:151], v80 offset:4608
	v_cvt_pk_bf16_f32 v2, v180, v181
	v_cvt_pk_bf16_f32 v3, v182, v183
	v_cvt_pk_bf16_f32 v4, v184, v185
	v_cvt_pk_bf16_f32 v5, v186, v187
	v_cvt_pk_bf16_f32 v6, v188, v189
	v_cvt_pk_bf16_f32 v7, v190, v191
	v_cvt_pk_bf16_f32 v8, v192, v193
	v_cvt_pk_bf16_f32 v9, v194, v195
	global_load_dwordx4 v[180:183], v72, s[74:75]
	global_load_dwordx4 v[184:187], v72, s[74:75] offset:16
	global_load_dwordx4 v[188:191], v72, s[74:75] offset:128
	global_load_dwordx4 v[192:195], v72, s[74:75] offset:144
	s_add_u32 s74, s74, 0x40000
	s_addc_u32 s75, s75, 0
	s_waitcnt lgkmcnt(0)
	v_mfma_f32_16x16x32_bf16 v[148:151], v[2:5], v[64:67], v[148:151]
	v_mfma_f32_16x16x32_bf16 v[148:151], v[6:9], v[68:71], v[148:151]
	s_waitcnt vmcnt(20)
	ds_read_b128 v[152:155], v80 offset:5120
	v_cvt_pk_bf16_f32 v2, v200, v201
	v_cvt_pk_bf16_f32 v3, v202, v203
	v_cvt_pk_bf16_f32 v4, v204, v205
	v_cvt_pk_bf16_f32 v5, v206, v207
	v_cvt_pk_bf16_f32 v6, v208, v209
	v_cvt_pk_bf16_f32 v7, v210, v211
	v_cvt_pk_bf16_f32 v8, v212, v213
	v_cvt_pk_bf16_f32 v9, v214, v215
	s_waitcnt lgkmcnt(0)
	v_mfma_f32_16x16x32_bf16 v[152:155], v[2:5], v[64:67], v[152:155]
	v_mfma_f32_16x16x32_bf16 v[152:155], v[6:9], v[68:71], v[152:155]
	s_waitcnt vmcnt(16)
	ds_read_b128 v[156:159], v80 offset:5632
	v_cvt_pk_bf16_f32 v2, v216, v217
	v_cvt_pk_bf16_f32 v3, v218, v219
	v_cvt_pk_bf16_f32 v4, v220, v221
	v_cvt_pk_bf16_f32 v5, v222, v223
	v_cvt_pk_bf16_f32 v6, v224, v225
	v_cvt_pk_bf16_f32 v7, v226, v227
	v_cvt_pk_bf16_f32 v8, v228, v229
	v_cvt_pk_bf16_f32 v9, v230, v231
	s_waitcnt lgkmcnt(0)
	v_mfma_f32_16x16x32_bf16 v[156:159], v[2:5], v[64:67], v[156:159]
	v_mfma_f32_16x16x32_bf16 v[156:159], v[6:9], v[68:71], v[156:159]
	s_waitcnt vmcnt(12)
	ds_read_b128 v[160:163], v80 offset:6144
	v_cvt_pk_bf16_f32 v2, v16, v17
	v_cvt_pk_bf16_f32 v3, v18, v19
	v_cvt_pk_bf16_f32 v4, v20, v21
	v_cvt_pk_bf16_f32 v5, v22, v23
	v_cvt_pk_bf16_f32 v6, v24, v25
	v_cvt_pk_bf16_f32 v7, v26, v27
	v_cvt_pk_bf16_f32 v8, v28, v29
	v_cvt_pk_bf16_f32 v9, v30, v31
	s_waitcnt lgkmcnt(0)
	v_mfma_f32_16x16x32_bf16 v[160:163], v[2:5], v[64:67], v[160:163]
	v_mfma_f32_16x16x32_bf16 v[160:163], v[6:9], v[68:71], v[160:163]
	s_waitcnt vmcnt(8)
	ds_read_b128 v[164:167], v80 offset:6656
	v_cvt_pk_bf16_f32 v2, v32, v33
	v_cvt_pk_bf16_f32 v3, v34, v35
	v_cvt_pk_bf16_f32 v4, v36, v37
	v_cvt_pk_bf16_f32 v5, v38, v39
	v_cvt_pk_bf16_f32 v6, v40, v41
	v_cvt_pk_bf16_f32 v7, v42, v43
	v_cvt_pk_bf16_f32 v8, v44, v45
	v_cvt_pk_bf16_f32 v9, v46, v47
	s_waitcnt lgkmcnt(0)
	v_mfma_f32_16x16x32_bf16 v[164:167], v[2:5], v[64:67], v[164:167]
	v_mfma_f32_16x16x32_bf16 v[164:167], v[6:9], v[68:71], v[164:167]
	s_waitcnt vmcnt(4)
	ds_read_b128 v[168:171], v80 offset:7168
	v_cvt_pk_bf16_f32 v2, v48, v49
	v_cvt_pk_bf16_f32 v3, v50, v51
	v_cvt_pk_bf16_f32 v4, v52, v53
	v_cvt_pk_bf16_f32 v5, v54, v55
	v_cvt_pk_bf16_f32 v6, v56, v57
	v_cvt_pk_bf16_f32 v7, v58, v59
	v_cvt_pk_bf16_f32 v8, v60, v61
	v_cvt_pk_bf16_f32 v9, v62, v63
	s_waitcnt lgkmcnt(0)
	v_mfma_f32_16x16x32_bf16 v[168:171], v[2:5], v[64:67], v[168:171]
	v_mfma_f32_16x16x32_bf16 v[168:171], v[6:9], v[68:71], v[168:171]
	s_waitcnt vmcnt(0)
	ds_read_b128 v[172:175], v80 offset:7680
	v_cvt_pk_bf16_f32 v2, v180, v181
	v_cvt_pk_bf16_f32 v3, v182, v183
	v_cvt_pk_bf16_f32 v4, v184, v185
	v_cvt_pk_bf16_f32 v5, v186, v187
	v_cvt_pk_bf16_f32 v6, v188, v189
	v_cvt_pk_bf16_f32 v7, v190, v191
	v_cvt_pk_bf16_f32 v8, v192, v193
	v_cvt_pk_bf16_f32 v9, v194, v195
	s_waitcnt lgkmcnt(0)
	v_mfma_f32_16x16x32_bf16 v[172:175], v[2:5], v[64:67], v[172:175]
	v_mfma_f32_16x16x32_bf16 v[172:175], v[6:9], v[68:71], v[172:175]
	s_cmp_lg_u32 s72, 0
	s_cbranch_scc1 .Lsa_t16_skip
	v_mov_b32_e32 v105, 0x2010
	v_lshl_add_u32 v105, v75, 4, v105
	ds_read_b128 v[176:179], v105
	v_cvt_pk_bf16_f32 v2, v232, v233
	v_cvt_pk_bf16_f32 v3, v234, v235
	v_cvt_pk_bf16_f32 v4, v236, v237
	v_cvt_pk_bf16_f32 v5, v238, v239
	v_cvt_pk_bf16_f32 v6, v240, v241
	v_cvt_pk_bf16_f32 v7, v242, v243
	v_cvt_pk_bf16_f32 v8, v244, v245
	v_cvt_pk_bf16_f32 v9, v246, v247
	global_load_dword v232, v73, s[84:85] offset:-4096
	global_load_dword v233, v73, s[84:85] offset:-2048
	global_load_dword v234, v73, s[84:85] offset:0
	global_load_dword v235, v73, s[84:85] offset:2048
	global_load_dword v236, v73, s[84:85] offset:-4032
	global_load_dword v237, v73, s[84:85] offset:-1984
	global_load_dword v238, v73, s[84:85] offset:64
	global_load_dword v239, v73, s[84:85] offset:2112
	global_load_dword v240, v73, s[84:85] offset:-3968
	global_load_dword v241, v73, s[84:85] offset:-1920
	global_load_dword v242, v73, s[84:85] offset:128
	global_load_dword v243, v73, s[84:85] offset:2176
	global_load_dword v244, v73, s[84:85] offset:-3904
	global_load_dword v245, v73, s[84:85] offset:-1856
	global_load_dword v246, v73, s[84:85] offset:192
	global_load_dword v247, v73, s[84:85] offset:2240
	s_waitcnt lgkmcnt(0)
	v_mfma_f32_16x16x32_bf16 v[176:179], v[2:5], v[64:67], v[176:179]
	v_mfma_f32_16x16x32_bf16 v[176:179], v[6:9], v[68:71], v[176:179]
	v_lshlrev_b32_e32 v105, 2, v75
	s_nop 7
	s_nop 1
	v_add_u32_e32 v106, 0, v105
	v_cmp_gt_u32_e32 vcc, v106, v77
	s_nop 1
	v_cndmask_b32_e32 v176, v176, v101, vcc
	v_add_u32_e32 v106, 1, v105
	v_cmp_gt_u32_e32 vcc, v106, v77
	s_nop 1
	v_cndmask_b32_e32 v177, v177, v101, vcc
	v_add_u32_e32 v106, 2, v105
	v_cmp_gt_u32_e32 vcc, v106, v77
	s_nop 1
	v_cndmask_b32_e32 v178, v178, v101, vcc
	v_add_u32_e32 v106, 3, v105
	v_cmp_gt_u32_e32 vcc, v106, v77
	s_nop 1
	v_cndmask_b32_e32 v179, v179, v101, vcc
.Lsa_t16_skip:
	global_load_dword v16, v73, s[76:77] offset:-4096
	global_load_dword v17, v73, s[76:77] offset:-2048
	global_load_dword v18, v73, s[76:77] offset:0
	global_load_dword v19, v73, s[76:77] offset:2048
	global_load_dword v20, v73, s[78:79] offset:-4096
	global_load_dword v21, v73, s[78:79] offset:-2048
	global_load_dword v22, v73, s[78:79] offset:0
	global_load_dword v23, v73, s[78:79] offset:2048
	global_load_dword v24, v73, s[76:77] offset:-4032
	global_load_dword v25, v73, s[76:77] offset:-1984
	global_load_dword v26, v73, s[76:77] offset:64
	global_load_dword v27, v73, s[76:77] offset:2112
	global_load_dword v28, v73, s[78:79] offset:-4032
	global_load_dword v29, v73, s[78:79] offset:-1984
	global_load_dword v30, v73, s[78:79] offset:64
	global_load_dword v31, v73, s[78:79] offset:2112
	global_load_dword v32, v73, s[76:77] offset:-3968
	global_load_dword v33, v73, s[76:77] offset:-1920
	global_load_dword v34, v73, s[76:77] offset:128
	global_load_dword v35, v73, s[76:77] offset:2176
	global_load_dword v36, v73, s[78:79] offset:-3968
	global_load_dword v37, v73, s[78:79] offset:-1920
	global_load_dword v38, v73, s[78:79] offset:128
	global_load_dword v39, v73, s[78:79] offset:2176
	global_load_dword v40, v73, s[76:77] offset:-3904
	global_load_dword v41, v73, s[76:77] offset:-1856
	global_load_dword v42, v73, s[76:77] offset:192
	global_load_dword v43, v73, s[76:77] offset:2240
	global_load_dword v44, v73, s[78:79] offset:-3904
	global_load_dword v45, v73, s[78:79] offset:-1856
	global_load_dword v46, v73, s[78:79] offset:192
	global_load_dword v47, v73, s[78:79] offset:2240
	s_add_u32 s76, s76, 0x80000
	s_addc_u32 s77, s77, 0
	s_add_u32 s78, s78, 0x80000
	s_addc_u32 s79, s79, 0
	global_load_dword v48, v73, s[76:77] offset:-4096
	global_load_dword v49, v73, s[76:77] offset:-2048
	global_load_dword v50, v73, s[76:77] offset:0
	global_load_dword v51, v73, s[76:77] offset:2048
	global_load_dword v52, v73, s[78:79] offset:-4096
	global_load_dword v53, v73, s[78:79] offset:-2048
	global_load_dword v54, v73, s[78:79] offset:0
	global_load_dword v55, v73, s[78:79] offset:2048
	global_load_dword v56, v73, s[76:77] offset:-4032
	global_load_dword v57, v73, s[76:77] offset:-1984
	global_load_dword v58, v73, s[76:77] offset:64
	global_load_dword v59, v73, s[76:77] offset:2112
	global_load_dword v60, v73, s[78:79] offset:-4032
	global_load_dword v61, v73, s[78:79] offset:-1984
	global_load_dword v62, v73, s[78:79] offset:64
	global_load_dword v63, v73, s[78:79] offset:2112
	s_nop 7
	s_nop 1
	v_max3_f32 v248, v112, v113, v114
	v_max3_f32 v248, v248, v115, v116
	v_max3_f32 v248, v248, v117, v118
	v_max3_f32 v248, v248, v119, v120
	v_max3_f32 v248, v248, v121, v122
	v_max3_f32 v248, v248, v123, v124
	v_max3_f32 v248, v248, v125, v126
	v_max3_f32 v248, v248, v127, v128
	v_max3_f32 v248, v248, v129, v130
	v_max3_f32 v248, v248, v131, v132
	v_max3_f32 v248, v248, v133, v134
	v_max3_f32 v248, v248, v135, v136
	v_max3_f32 v248, v248, v137, v138
	v_max3_f32 v248, v248, v139, v140
	v_max3_f32 v248, v248, v141, v142
	v_max3_f32 v248, v248, v143, v144
	v_max3_f32 v248, v248, v145, v146
	v_max3_f32 v248, v248, v147, v148
	v_max3_f32 v248, v248, v149, v150
	v_max3_f32 v248, v248, v151, v152
	v_max3_f32 v248, v248, v153, v154
	v_max3_f32 v248, v248, v155, v156
	v_max3_f32 v248, v248, v157, v158
	v_max3_f32 v248, v248, v159, v160
	v_max3_f32 v248, v248, v161, v162
	v_max3_f32 v248, v248, v163, v164
	v_max3_f32 v248, v248, v165, v166
	v_max3_f32 v248, v248, v167, v168
	v_max3_f32 v248, v248, v169, v170
	v_max3_f32 v248, v248, v171, v172
	v_max3_f32 v248, v248, v173, v174
	v_max3_f32 v248, v248, v175, v176
	v_max3_f32 v248, v248, v177, v178
	v_max3_f32 v248, v248, v179, v179
	ds_write_b32 v81, v248 offset:49168
	v_lshlrev_b32_e32 v105, 2, v77
	v_add_u32_e32 v105, 0xc010, v105
	v_add_u32_e32 v106, 64, v105
	v_add_u32_e32 v107, 0x80, v105
	v_add_u32_e32 v108, 0xc0, v105
	s_waitcnt lgkmcnt(0)
	s_barrier
	ds_read2st64_b32 v[200:201], v105 offset0:0 offset1:1
	ds_read2st64_b32 v[202:203], v105 offset0:2 offset1:3
	ds_read2st64_b32 v[204:205], v105 offset0:4 offset1:5
	ds_read2st64_b32 v[206:207], v105 offset0:6 offset1:7
	ds_read2st64_b32 v[208:209], v106 offset0:0 offset1:1
	ds_read2st64_b32 v[210:211], v106 offset0:2 offset1:3
	ds_read2st64_b32 v[212:213], v106 offset0:4 offset1:5
	ds_read2st64_b32 v[214:215], v106 offset0:6 offset1:7
	ds_read2st64_b32 v[216:217], v107 offset0:0 offset1:1
	ds_read2st64_b32 v[218:219], v107 offset0:2 offset1:3
	ds_read2st64_b32 v[220:221], v107 offset0:4 offset1:5
	ds_read2st64_b32 v[222:223], v107 offset0:6 offset1:7
	ds_read2st64_b32 v[224:225], v108 offset0:0 offset1:1
	ds_read2st64_b32 v[226:227], v108 offset0:2 offset1:3
	ds_read2st64_b32 v[228:229], v108 offset0:4 offset1:5
	ds_read2st64_b32 v[230:231], v108 offset0:6 offset1:7
	s_waitcnt lgkmcnt(0)
	v_max3_f32 v248, v200, v201, v202
	v_max3_f32 v248, v248, v203, v204
	v_max3_f32 v248, v248, v205, v206
	v_max3_f32 v248, v248, v207, v208
	v_max3_f32 v248, v248, v209, v210
	v_max3_f32 v248, v248, v211, v212
	v_max3_f32 v248, v248, v213, v214
	v_max3_f32 v248, v248, v215, v216
	v_max3_f32 v248, v248, v217, v218
	v_max3_f32 v248, v248, v219, v220
	v_max3_f32 v248, v248, v221, v222
	v_max3_f32 v248, v248, v223, v224
	v_max3_f32 v248, v248, v225, v226
	v_max3_f32 v248, v248, v227, v228
	v_max3_f32 v248, v248, v229, v230
	v_max3_f32 v248, v248, v231, v231
	v_mov_b32_e32 v249, 0
	v_sub_f32_e32 v112, v112, v248
	v_sub_f32_e32 v113, v113, v248
	v_sub_f32_e32 v114, v114, v248
	v_sub_f32_e32 v115, v115, v248
	v_cmp_gt_f32_e64 s[24:25], s61, v112
	v_cmp_gt_f32_e64 s[26:27], s61, v113
	v_cmp_gt_f32_e64 s[28:29], s61, v114
	v_cmp_gt_f32_e64 s[34:35], s61, v115
	v_cndmask_b32_e64 v200, 0, v102, s[24:25]
	v_cndmask_b32_e64 v201, 0, v102, s[26:27]
	v_cndmask_b32_e64 v202, 0, v102, s[28:29]
	v_cndmask_b32_e64 v203, 0, v102, s[34:35]
	v_add_f32_e32 v112, v112, v200
	v_add_f32_e32 v113, v113, v201
	v_add_f32_e32 v114, v114, v202
	v_add_f32_e32 v115, v115, v203
	v_exp_f32_e32 v112, v112
	v_exp_f32_e32 v113, v113
	v_exp_f32_e32 v114, v114
	v_exp_f32_e32 v115, v115
	v_cndmask_b32_e64 v200, 0, v103, s[24:25]
	v_cndmask_b32_e64 v201, 0, v103, s[26:27]
	v_cndmask_b32_e64 v202, 0, v103, s[28:29]
	v_cndmask_b32_e64 v203, 0, v103, s[34:35]
	v_ldexp_f32 v112, v112, v200
	v_ldexp_f32 v113, v113, v201
	v_ldexp_f32 v114, v114, v202
	v_ldexp_f32 v115, v115, v203
	v_add_f32_e32 v249, v249, v112
	v_add_f32_e32 v249, v249, v113
	v_add_f32_e32 v249, v249, v114
	v_add_f32_e32 v249, v249, v115
	v_sub_f32_e32 v116, v116, v248
	v_sub_f32_e32 v117, v117, v248
	v_sub_f32_e32 v118, v118, v248
	v_sub_f32_e32 v119, v119, v248
	v_cmp_gt_f32_e64 s[24:25], s61, v116
	v_cmp_gt_f32_e64 s[26:27], s61, v117
	v_cmp_gt_f32_e64 s[28:29], s61, v118
	v_cmp_gt_f32_e64 s[34:35], s61, v119
	v_cndmask_b32_e64 v200, 0, v102, s[24:25]
	v_cndmask_b32_e64 v201, 0, v102, s[26:27]
	v_cndmask_b32_e64 v202, 0, v102, s[28:29]
	v_cndmask_b32_e64 v203, 0, v102, s[34:35]
	v_add_f32_e32 v116, v116, v200
	v_add_f32_e32 v117, v117, v201
	v_add_f32_e32 v118, v118, v202
	v_add_f32_e32 v119, v119, v203
	v_exp_f32_e32 v116, v116
	v_exp_f32_e32 v117, v117
	v_exp_f32_e32 v118, v118
	v_exp_f32_e32 v119, v119
	v_cndmask_b32_e64 v200, 0, v103, s[24:25]
	v_cndmask_b32_e64 v201, 0, v103, s[26:27]
	v_cndmask_b32_e64 v202, 0, v103, s[28:29]
	v_cndmask_b32_e64 v203, 0, v103, s[34:35]
	v_ldexp_f32 v116, v116, v200
	v_ldexp_f32 v117, v117, v201
	v_ldexp_f32 v118, v118, v202
	v_ldexp_f32 v119, v119, v203
	v_add_f32_e32 v249, v249, v116
	v_add_f32_e32 v249, v249, v117
	v_add_f32_e32 v249, v249, v118
	v_add_f32_e32 v249, v249, v119
	v_sub_f32_e32 v120, v120, v248
	v_sub_f32_e32 v121, v121, v248
	v_sub_f32_e32 v122, v122, v248
	v_sub_f32_e32 v123, v123, v248
	v_cmp_gt_f32_e64 s[24:25], s61, v120
	v_cmp_gt_f32_e64 s[26:27], s61, v121
	v_cmp_gt_f32_e64 s[28:29], s61, v122
	v_cmp_gt_f32_e64 s[34:35], s61, v123
	v_cndmask_b32_e64 v200, 0, v102, s[24:25]
	v_cndmask_b32_e64 v201, 0, v102, s[26:27]
	v_cndmask_b32_e64 v202, 0, v102, s[28:29]
	v_cndmask_b32_e64 v203, 0, v102, s[34:35]
	v_add_f32_e32 v120, v120, v200
	v_add_f32_e32 v121, v121, v201
	v_add_f32_e32 v122, v122, v202
	v_add_f32_e32 v123, v123, v203
	v_exp_f32_e32 v120, v120
	v_exp_f32_e32 v121, v121
	v_exp_f32_e32 v122, v122
	v_exp_f32_e32 v123, v123
	v_cndmask_b32_e64 v200, 0, v103, s[24:25]
	v_cndmask_b32_e64 v201, 0, v103, s[26:27]
	v_cndmask_b32_e64 v202, 0, v103, s[28:29]
	v_cndmask_b32_e64 v203, 0, v103, s[34:35]
	v_ldexp_f32 v120, v120, v200
	v_ldexp_f32 v121, v121, v201
	v_ldexp_f32 v122, v122, v202
	v_ldexp_f32 v123, v123, v203
	v_add_f32_e32 v249, v249, v120
	v_add_f32_e32 v249, v249, v121
	v_add_f32_e32 v249, v249, v122
	v_add_f32_e32 v249, v249, v123
	v_sub_f32_e32 v124, v124, v248
	v_sub_f32_e32 v125, v125, v248
	v_sub_f32_e32 v126, v126, v248
	v_sub_f32_e32 v127, v127, v248
	v_cmp_gt_f32_e64 s[24:25], s61, v124
	v_cmp_gt_f32_e64 s[26:27], s61, v125
	v_cmp_gt_f32_e64 s[28:29], s61, v126
	v_cmp_gt_f32_e64 s[34:35], s61, v127
	v_cndmask_b32_e64 v200, 0, v102, s[24:25]
	v_cndmask_b32_e64 v201, 0, v102, s[26:27]
	v_cndmask_b32_e64 v202, 0, v102, s[28:29]
	v_cndmask_b32_e64 v203, 0, v102, s[34:35]
	v_add_f32_e32 v124, v124, v200
	v_add_f32_e32 v125, v125, v201
	v_add_f32_e32 v126, v126, v202
	v_add_f32_e32 v127, v127, v203
	v_exp_f32_e32 v124, v124
	v_exp_f32_e32 v125, v125
	v_exp_f32_e32 v126, v126
	v_exp_f32_e32 v127, v127
	v_cndmask_b32_e64 v200, 0, v103, s[24:25]
	v_cndmask_b32_e64 v201, 0, v103, s[26:27]
	v_cndmask_b32_e64 v202, 0, v103, s[28:29]
	v_cndmask_b32_e64 v203, 0, v103, s[34:35]
	v_ldexp_f32 v124, v124, v200
	v_ldexp_f32 v125, v125, v201
	v_ldexp_f32 v126, v126, v202
	v_ldexp_f32 v127, v127, v203
	v_add_f32_e32 v249, v249, v124
	v_add_f32_e32 v249, v249, v125
	v_add_f32_e32 v249, v249, v126
	v_add_f32_e32 v249, v249, v127
	v_sub_f32_e32 v128, v128, v248
	v_sub_f32_e32 v129, v129, v248
	v_sub_f32_e32 v130, v130, v248
	v_sub_f32_e32 v131, v131, v248
	v_cmp_gt_f32_e64 s[24:25], s61, v128
	v_cmp_gt_f32_e64 s[26:27], s61, v129
	v_cmp_gt_f32_e64 s[28:29], s61, v130
	v_cmp_gt_f32_e64 s[34:35], s61, v131
	v_cndmask_b32_e64 v200, 0, v102, s[24:25]
	v_cndmask_b32_e64 v201, 0, v102, s[26:27]
	v_cndmask_b32_e64 v202, 0, v102, s[28:29]
	v_cndmask_b32_e64 v203, 0, v102, s[34:35]
	v_add_f32_e32 v128, v128, v200
	v_add_f32_e32 v129, v129, v201
	v_add_f32_e32 v130, v130, v202
	v_add_f32_e32 v131, v131, v203
	v_exp_f32_e32 v128, v128
	v_exp_f32_e32 v129, v129
	v_exp_f32_e32 v130, v130
	v_exp_f32_e32 v131, v131
	v_cndmask_b32_e64 v200, 0, v103, s[24:25]
	v_cndmask_b32_e64 v201, 0, v103, s[26:27]
	v_cndmask_b32_e64 v202, 0, v103, s[28:29]
	v_cndmask_b32_e64 v203, 0, v103, s[34:35]
	v_ldexp_f32 v128, v128, v200
	v_ldexp_f32 v129, v129, v201
	v_ldexp_f32 v130, v130, v202
	v_ldexp_f32 v131, v131, v203
	v_add_f32_e32 v249, v249, v128
	v_add_f32_e32 v249, v249, v129
	v_add_f32_e32 v249, v249, v130
	v_add_f32_e32 v249, v249, v131
	v_sub_f32_e32 v132, v132, v248
	v_sub_f32_e32 v133, v133, v248
	v_sub_f32_e32 v134, v134, v248
	v_sub_f32_e32 v135, v135, v248
	v_cmp_gt_f32_e64 s[24:25], s61, v132
	v_cmp_gt_f32_e64 s[26:27], s61, v133
	v_cmp_gt_f32_e64 s[28:29], s61, v134
	v_cmp_gt_f32_e64 s[34:35], s61, v135
	v_cndmask_b32_e64 v200, 0, v102, s[24:25]
	v_cndmask_b32_e64 v201, 0, v102, s[26:27]
	v_cndmask_b32_e64 v202, 0, v102, s[28:29]
	v_cndmask_b32_e64 v203, 0, v102, s[34:35]
	v_add_f32_e32 v132, v132, v200
	v_add_f32_e32 v133, v133, v201
	v_add_f32_e32 v134, v134, v202
	v_add_f32_e32 v135, v135, v203
	v_exp_f32_e32 v132, v132
	v_exp_f32_e32 v133, v133
	v_exp_f32_e32 v134, v134
	v_exp_f32_e32 v135, v135
	v_cndmask_b32_e64 v200, 0, v103, s[24:25]
	v_cndmask_b32_e64 v201, 0, v103, s[26:27]
	v_cndmask_b32_e64 v202, 0, v103, s[28:29]
	v_cndmask_b32_e64 v203, 0, v103, s[34:35]
	v_ldexp_f32 v132, v132, v200
	v_ldexp_f32 v133, v133, v201
	v_ldexp_f32 v134, v134, v202
	v_ldexp_f32 v135, v135, v203
	v_add_f32_e32 v249, v249, v132
	v_add_f32_e32 v249, v249, v133
	v_add_f32_e32 v249, v249, v134
	v_add_f32_e32 v249, v249, v135
	v_sub_f32_e32 v136, v136, v248
	v_sub_f32_e32 v137, v137, v248
	v_sub_f32_e32 v138, v138, v248
	v_sub_f32_e32 v139, v139, v248
	v_cmp_gt_f32_e64 s[24:25], s61, v136
	v_cmp_gt_f32_e64 s[26:27], s61, v137
	v_cmp_gt_f32_e64 s[28:29], s61, v138
	v_cmp_gt_f32_e64 s[34:35], s61, v139
	v_cndmask_b32_e64 v200, 0, v102, s[24:25]
	v_cndmask_b32_e64 v201, 0, v102, s[26:27]
	v_cndmask_b32_e64 v202, 0, v102, s[28:29]
	v_cndmask_b32_e64 v203, 0, v102, s[34:35]
	v_add_f32_e32 v136, v136, v200
	v_add_f32_e32 v137, v137, v201
	v_add_f32_e32 v138, v138, v202
	v_add_f32_e32 v139, v139, v203
	v_exp_f32_e32 v136, v136
	v_exp_f32_e32 v137, v137
	v_exp_f32_e32 v138, v138
	v_exp_f32_e32 v139, v139
	v_cndmask_b32_e64 v200, 0, v103, s[24:25]
	v_cndmask_b32_e64 v201, 0, v103, s[26:27]
	v_cndmask_b32_e64 v202, 0, v103, s[28:29]
	v_cndmask_b32_e64 v203, 0, v103, s[34:35]
	v_ldexp_f32 v136, v136, v200
	v_ldexp_f32 v137, v137, v201
	v_ldexp_f32 v138, v138, v202
	v_ldexp_f32 v139, v139, v203
	v_add_f32_e32 v249, v249, v136
	v_add_f32_e32 v249, v249, v137
	v_add_f32_e32 v249, v249, v138
	v_add_f32_e32 v249, v249, v139
	v_sub_f32_e32 v140, v140, v248
	v_sub_f32_e32 v141, v141, v248
	v_sub_f32_e32 v142, v142, v248
	v_sub_f32_e32 v143, v143, v248
	v_cmp_gt_f32_e64 s[24:25], s61, v140
	v_cmp_gt_f32_e64 s[26:27], s61, v141
	v_cmp_gt_f32_e64 s[28:29], s61, v142
	v_cmp_gt_f32_e64 s[34:35], s61, v143
	v_cndmask_b32_e64 v200, 0, v102, s[24:25]
	v_cndmask_b32_e64 v201, 0, v102, s[26:27]
	v_cndmask_b32_e64 v202, 0, v102, s[28:29]
	v_cndmask_b32_e64 v203, 0, v102, s[34:35]
	v_add_f32_e32 v140, v140, v200
	v_add_f32_e32 v141, v141, v201
	v_add_f32_e32 v142, v142, v202
	v_add_f32_e32 v143, v143, v203
	v_exp_f32_e32 v140, v140
	v_exp_f32_e32 v141, v141
	v_exp_f32_e32 v142, v142
	v_exp_f32_e32 v143, v143
	v_cndmask_b32_e64 v200, 0, v103, s[24:25]
	v_cndmask_b32_e64 v201, 0, v103, s[26:27]
	v_cndmask_b32_e64 v202, 0, v103, s[28:29]
	v_cndmask_b32_e64 v203, 0, v103, s[34:35]
	v_ldexp_f32 v140, v140, v200
	v_ldexp_f32 v141, v141, v201
	v_ldexp_f32 v142, v142, v202
	v_ldexp_f32 v143, v143, v203
	v_add_f32_e32 v249, v249, v140
	v_add_f32_e32 v249, v249, v141
	v_add_f32_e32 v249, v249, v142
	v_add_f32_e32 v249, v249, v143
	v_sub_f32_e32 v144, v144, v248
	v_sub_f32_e32 v145, v145, v248
	v_sub_f32_e32 v146, v146, v248
	v_sub_f32_e32 v147, v147, v248
	v_cmp_gt_f32_e64 s[24:25], s61, v144
	v_cmp_gt_f32_e64 s[26:27], s61, v145
	v_cmp_gt_f32_e64 s[28:29], s61, v146
	v_cmp_gt_f32_e64 s[34:35], s61, v147
	v_cndmask_b32_e64 v200, 0, v102, s[24:25]
	v_cndmask_b32_e64 v201, 0, v102, s[26:27]
	v_cndmask_b32_e64 v202, 0, v102, s[28:29]
	v_cndmask_b32_e64 v203, 0, v102, s[34:35]
	v_add_f32_e32 v144, v144, v200
	v_add_f32_e32 v145, v145, v201
	v_add_f32_e32 v146, v146, v202
	v_add_f32_e32 v147, v147, v203
	v_exp_f32_e32 v144, v144
	v_exp_f32_e32 v145, v145
	v_exp_f32_e32 v146, v146
	v_exp_f32_e32 v147, v147
	v_cndmask_b32_e64 v200, 0, v103, s[24:25]
	v_cndmask_b32_e64 v201, 0, v103, s[26:27]
	v_cndmask_b32_e64 v202, 0, v103, s[28:29]
	v_cndmask_b32_e64 v203, 0, v103, s[34:35]
	v_ldexp_f32 v144, v144, v200
	v_ldexp_f32 v145, v145, v201
	v_ldexp_f32 v146, v146, v202
	v_ldexp_f32 v147, v147, v203
	v_add_f32_e32 v249, v249, v144
	v_add_f32_e32 v249, v249, v145
	v_add_f32_e32 v249, v249, v146
	v_add_f32_e32 v249, v249, v147
	v_sub_f32_e32 v148, v148, v248
	v_sub_f32_e32 v149, v149, v248
	v_sub_f32_e32 v150, v150, v248
	v_sub_f32_e32 v151, v151, v248
	v_cmp_gt_f32_e64 s[24:25], s61, v148
	v_cmp_gt_f32_e64 s[26:27], s61, v149
	v_cmp_gt_f32_e64 s[28:29], s61, v150
	v_cmp_gt_f32_e64 s[34:35], s61, v151
	v_cndmask_b32_e64 v200, 0, v102, s[24:25]
	v_cndmask_b32_e64 v201, 0, v102, s[26:27]
	v_cndmask_b32_e64 v202, 0, v102, s[28:29]
	v_cndmask_b32_e64 v203, 0, v102, s[34:35]
	v_add_f32_e32 v148, v148, v200
	v_add_f32_e32 v149, v149, v201
	v_add_f32_e32 v150, v150, v202
	v_add_f32_e32 v151, v151, v203
	v_exp_f32_e32 v148, v148
	v_exp_f32_e32 v149, v149
	v_exp_f32_e32 v150, v150
	v_exp_f32_e32 v151, v151
	v_cndmask_b32_e64 v200, 0, v103, s[24:25]
	v_cndmask_b32_e64 v201, 0, v103, s[26:27]
	v_cndmask_b32_e64 v202, 0, v103, s[28:29]
	v_cndmask_b32_e64 v203, 0, v103, s[34:35]
	v_ldexp_f32 v148, v148, v200
	v_ldexp_f32 v149, v149, v201
	v_ldexp_f32 v150, v150, v202
	v_ldexp_f32 v151, v151, v203
	v_add_f32_e32 v249, v249, v148
	v_add_f32_e32 v249, v249, v149
	v_add_f32_e32 v249, v249, v150
	v_add_f32_e32 v249, v249, v151
	v_sub_f32_e32 v152, v152, v248
	v_sub_f32_e32 v153, v153, v248
	v_sub_f32_e32 v154, v154, v248
	v_sub_f32_e32 v155, v155, v248
	v_cmp_gt_f32_e64 s[24:25], s61, v152
	v_cmp_gt_f32_e64 s[26:27], s61, v153
	v_cmp_gt_f32_e64 s[28:29], s61, v154
	v_cmp_gt_f32_e64 s[34:35], s61, v155
	v_cndmask_b32_e64 v200, 0, v102, s[24:25]
	v_cndmask_b32_e64 v201, 0, v102, s[26:27]
	v_cndmask_b32_e64 v202, 0, v102, s[28:29]
	v_cndmask_b32_e64 v203, 0, v102, s[34:35]
	v_add_f32_e32 v152, v152, v200
	v_add_f32_e32 v153, v153, v201
	v_add_f32_e32 v154, v154, v202
	v_add_f32_e32 v155, v155, v203
	v_exp_f32_e32 v152, v152
	v_exp_f32_e32 v153, v153
	v_exp_f32_e32 v154, v154
	v_exp_f32_e32 v155, v155
	v_cndmask_b32_e64 v200, 0, v103, s[24:25]
	v_cndmask_b32_e64 v201, 0, v103, s[26:27]
	v_cndmask_b32_e64 v202, 0, v103, s[28:29]
	v_cndmask_b32_e64 v203, 0, v103, s[34:35]
	v_ldexp_f32 v152, v152, v200
	v_ldexp_f32 v153, v153, v201
	v_ldexp_f32 v154, v154, v202
	v_ldexp_f32 v155, v155, v203
	v_add_f32_e32 v249, v249, v152
	v_add_f32_e32 v249, v249, v153
	v_add_f32_e32 v249, v249, v154
	v_add_f32_e32 v249, v249, v155
	v_sub_f32_e32 v156, v156, v248
	v_sub_f32_e32 v157, v157, v248
	v_sub_f32_e32 v158, v158, v248
	v_sub_f32_e32 v159, v159, v248
	v_cmp_gt_f32_e64 s[24:25], s61, v156
	v_cmp_gt_f32_e64 s[26:27], s61, v157
	v_cmp_gt_f32_e64 s[28:29], s61, v158
	v_cmp_gt_f32_e64 s[34:35], s61, v159
	v_cndmask_b32_e64 v200, 0, v102, s[24:25]
	v_cndmask_b32_e64 v201, 0, v102, s[26:27]
	v_cndmask_b32_e64 v202, 0, v102, s[28:29]
	v_cndmask_b32_e64 v203, 0, v102, s[34:35]
	v_add_f32_e32 v156, v156, v200
	v_add_f32_e32 v157, v157, v201
	v_add_f32_e32 v158, v158, v202
	v_add_f32_e32 v159, v159, v203
	v_exp_f32_e32 v156, v156
	v_exp_f32_e32 v157, v157
	v_exp_f32_e32 v158, v158
	v_exp_f32_e32 v159, v159
	v_cndmask_b32_e64 v200, 0, v103, s[24:25]
	v_cndmask_b32_e64 v201, 0, v103, s[26:27]
	v_cndmask_b32_e64 v202, 0, v103, s[28:29]
	v_cndmask_b32_e64 v203, 0, v103, s[34:35]
	v_ldexp_f32 v156, v156, v200
	v_ldexp_f32 v157, v157, v201
	v_ldexp_f32 v158, v158, v202
	v_ldexp_f32 v159, v159, v203
	v_add_f32_e32 v249, v249, v156
	v_add_f32_e32 v249, v249, v157
	v_add_f32_e32 v249, v249, v158
	v_add_f32_e32 v249, v249, v159
	v_sub_f32_e32 v160, v160, v248
	v_sub_f32_e32 v161, v161, v248
	v_sub_f32_e32 v162, v162, v248
	v_sub_f32_e32 v163, v163, v248
	v_cmp_gt_f32_e64 s[24:25], s61, v160
	v_cmp_gt_f32_e64 s[26:27], s61, v161
	v_cmp_gt_f32_e64 s[28:29], s61, v162
	v_cmp_gt_f32_e64 s[34:35], s61, v163
	v_cndmask_b32_e64 v200, 0, v102, s[24:25]
	v_cndmask_b32_e64 v201, 0, v102, s[26:27]
	v_cndmask_b32_e64 v202, 0, v102, s[28:29]
	v_cndmask_b32_e64 v203, 0, v102, s[34:35]
	v_add_f32_e32 v160, v160, v200
	v_add_f32_e32 v161, v161, v201
	v_add_f32_e32 v162, v162, v202
	v_add_f32_e32 v163, v163, v203
	v_exp_f32_e32 v160, v160
	v_exp_f32_e32 v161, v161
	v_exp_f32_e32 v162, v162
	v_exp_f32_e32 v163, v163
	v_cndmask_b32_e64 v200, 0, v103, s[24:25]
	v_cndmask_b32_e64 v201, 0, v103, s[26:27]
	v_cndmask_b32_e64 v202, 0, v103, s[28:29]
	v_cndmask_b32_e64 v203, 0, v103, s[34:35]
	v_ldexp_f32 v160, v160, v200
	v_ldexp_f32 v161, v161, v201
	v_ldexp_f32 v162, v162, v202
	v_ldexp_f32 v163, v163, v203
	v_add_f32_e32 v249, v249, v160
	v_add_f32_e32 v249, v249, v161
	v_add_f32_e32 v249, v249, v162
	v_add_f32_e32 v249, v249, v163
	v_sub_f32_e32 v164, v164, v248
	v_sub_f32_e32 v165, v165, v248
	v_sub_f32_e32 v166, v166, v248
	v_sub_f32_e32 v167, v167, v248
	v_cmp_gt_f32_e64 s[24:25], s61, v164
	v_cmp_gt_f32_e64 s[26:27], s61, v165
	v_cmp_gt_f32_e64 s[28:29], s61, v166
	v_cmp_gt_f32_e64 s[34:35], s61, v167
	v_cndmask_b32_e64 v200, 0, v102, s[24:25]
	v_cndmask_b32_e64 v201, 0, v102, s[26:27]
	v_cndmask_b32_e64 v202, 0, v102, s[28:29]
	v_cndmask_b32_e64 v203, 0, v102, s[34:35]
	v_add_f32_e32 v164, v164, v200
	v_add_f32_e32 v165, v165, v201
	v_add_f32_e32 v166, v166, v202
	v_add_f32_e32 v167, v167, v203
	v_exp_f32_e32 v164, v164
	v_exp_f32_e32 v165, v165
	v_exp_f32_e32 v166, v166
	v_exp_f32_e32 v167, v167
	v_cndmask_b32_e64 v200, 0, v103, s[24:25]
	v_cndmask_b32_e64 v201, 0, v103, s[26:27]
	v_cndmask_b32_e64 v202, 0, v103, s[28:29]
	v_cndmask_b32_e64 v203, 0, v103, s[34:35]
	v_ldexp_f32 v164, v164, v200
	v_ldexp_f32 v165, v165, v201
	v_ldexp_f32 v166, v166, v202
	v_ldexp_f32 v167, v167, v203
	v_add_f32_e32 v249, v249, v164
	v_add_f32_e32 v249, v249, v165
	v_add_f32_e32 v249, v249, v166
	v_add_f32_e32 v249, v249, v167
	v_sub_f32_e32 v168, v168, v248
	v_sub_f32_e32 v169, v169, v248
	v_sub_f32_e32 v170, v170, v248
	v_sub_f32_e32 v171, v171, v248
	v_cmp_gt_f32_e64 s[24:25], s61, v168
	v_cmp_gt_f32_e64 s[26:27], s61, v169
	v_cmp_gt_f32_e64 s[28:29], s61, v170
	v_cmp_gt_f32_e64 s[34:35], s61, v171
	v_cndmask_b32_e64 v200, 0, v102, s[24:25]
	v_cndmask_b32_e64 v201, 0, v102, s[26:27]
	v_cndmask_b32_e64 v202, 0, v102, s[28:29]
	v_cndmask_b32_e64 v203, 0, v102, s[34:35]
	v_add_f32_e32 v168, v168, v200
	v_add_f32_e32 v169, v169, v201
	v_add_f32_e32 v170, v170, v202
	v_add_f32_e32 v171, v171, v203
	v_exp_f32_e32 v168, v168
	v_exp_f32_e32 v169, v169
	v_exp_f32_e32 v170, v170
	v_exp_f32_e32 v171, v171
	v_cndmask_b32_e64 v200, 0, v103, s[24:25]
	v_cndmask_b32_e64 v201, 0, v103, s[26:27]
	v_cndmask_b32_e64 v202, 0, v103, s[28:29]
	v_cndmask_b32_e64 v203, 0, v103, s[34:35]
	v_ldexp_f32 v168, v168, v200
	v_ldexp_f32 v169, v169, v201
	v_ldexp_f32 v170, v170, v202
	v_ldexp_f32 v171, v171, v203
	v_add_f32_e32 v249, v249, v168
	v_add_f32_e32 v249, v249, v169
	v_add_f32_e32 v249, v249, v170
	v_add_f32_e32 v249, v249, v171
	v_sub_f32_e32 v172, v172, v248
	v_sub_f32_e32 v173, v173, v248
	v_sub_f32_e32 v174, v174, v248
	v_sub_f32_e32 v175, v175, v248
	v_cmp_gt_f32_e64 s[24:25], s61, v172
	v_cmp_gt_f32_e64 s[26:27], s61, v173
	v_cmp_gt_f32_e64 s[28:29], s61, v174
	v_cmp_gt_f32_e64 s[34:35], s61, v175
	v_cndmask_b32_e64 v200, 0, v102, s[24:25]
	v_cndmask_b32_e64 v201, 0, v102, s[26:27]
	v_cndmask_b32_e64 v202, 0, v102, s[28:29]
	v_cndmask_b32_e64 v203, 0, v102, s[34:35]
	v_add_f32_e32 v172, v172, v200
	v_add_f32_e32 v173, v173, v201
	v_add_f32_e32 v174, v174, v202
	v_add_f32_e32 v175, v175, v203
	v_exp_f32_e32 v172, v172
	v_exp_f32_e32 v173, v173
	v_exp_f32_e32 v174, v174
	v_exp_f32_e32 v175, v175
	v_cndmask_b32_e64 v200, 0, v103, s[24:25]
	v_cndmask_b32_e64 v201, 0, v103, s[26:27]
	v_cndmask_b32_e64 v202, 0, v103, s[28:29]
	v_cndmask_b32_e64 v203, 0, v103, s[34:35]
	v_ldexp_f32 v172, v172, v200
	v_ldexp_f32 v173, v173, v201
	v_ldexp_f32 v174, v174, v202
	v_ldexp_f32 v175, v175, v203
	v_add_f32_e32 v249, v249, v172
	v_add_f32_e32 v249, v249, v173
	v_add_f32_e32 v249, v249, v174
	v_add_f32_e32 v249, v249, v175
	v_sub_f32_e32 v176, v176, v248
	v_sub_f32_e32 v177, v177, v248
	v_sub_f32_e32 v178, v178, v248
	v_sub_f32_e32 v179, v179, v248
	v_cmp_gt_f32_e64 s[24:25], s61, v176
	v_cmp_gt_f32_e64 s[26:27], s61, v177
	v_cmp_gt_f32_e64 s[28:29], s61, v178
	v_cmp_gt_f32_e64 s[34:35], s61, v179
	v_cndmask_b32_e64 v200, 0, v102, s[24:25]
	v_cndmask_b32_e64 v201, 0, v102, s[26:27]
	v_cndmask_b32_e64 v202, 0, v102, s[28:29]
	v_cndmask_b32_e64 v203, 0, v102, s[34:35]
	v_add_f32_e32 v176, v176, v200
	v_add_f32_e32 v177, v177, v201
	v_add_f32_e32 v178, v178, v202
	v_add_f32_e32 v179, v179, v203
	v_exp_f32_e32 v176, v176
	v_exp_f32_e32 v177, v177
	v_exp_f32_e32 v178, v178
	v_exp_f32_e32 v179, v179
	v_cndmask_b32_e64 v200, 0, v103, s[24:25]
	v_cndmask_b32_e64 v201, 0, v103, s[26:27]
	v_cndmask_b32_e64 v202, 0, v103, s[28:29]
	v_cndmask_b32_e64 v203, 0, v103, s[34:35]
	v_ldexp_f32 v176, v176, v200
	v_ldexp_f32 v177, v177, v201
	v_ldexp_f32 v178, v178, v202
	v_ldexp_f32 v179, v179, v203
	v_add_f32_e32 v249, v249, v176
	v_add_f32_e32 v249, v249, v177
	v_add_f32_e32 v249, v249, v178
	v_add_f32_e32 v249, v249, v179
	ds_write_b32 v81, v249 offset:51216
	v_mov_b32_e32 v180, 0
	v_mov_b32_e32 v181, 0
	v_mov_b32_e32 v182, 0
	v_mov_b32_e32 v183, 0
	v_mov_b32_e32 v184, 0
	v_mov_b32_e32 v185, 0
	v_mov_b32_e32 v186, 0
	v_mov_b32_e32 v187, 0
	v_mov_b32_e32 v188, 0
	v_mov_b32_e32 v189, 0
	v_mov_b32_e32 v190, 0
	v_mov_b32_e32 v191, 0
	v_mov_b32_e32 v192, 0
	v_mov_b32_e32 v193, 0
	v_mov_b32_e32 v194, 0
	v_mov_b32_e32 v195, 0
	v_cvt_pk_bf16_f32 v10, v112, v113
	v_cvt_pk_bf16_f32 v11, v114, v115
	v_cvt_pk_bf16_f32 v12, v116, v117
	v_cvt_pk_bf16_f32 v13, v118, v119
	s_waitcnt vmcnt(40)
	v_cvt_pk_bf16_f32 v2, v16, v17
	v_cvt_pk_bf16_f32 v3, v18, v19
	v_cvt_pk_bf16_f32 v4, v20, v21
	v_cvt_pk_bf16_f32 v5, v22, v23
	global_load_dword v16, v73, s[76:77] offset:-3968
	global_load_dword v17, v73, s[76:77] offset:-1920
	global_load_dword v18, v73, s[76:77] offset:128
	global_load_dword v19, v73, s[76:77] offset:2176
	global_load_dword v20, v73, s[78:79] offset:-3968
	global_load_dword v21, v73, s[78:79] offset:-1920
	global_load_dword v22, v73, s[78:79] offset:128
	global_load_dword v23, v73, s[78:79] offset:2176
	v_mfma_f32_16x16x32_bf16 v[180:183], v[2:5], v[10:13], v[180:183]
	s_waitcnt vmcnt(40)
	v_cvt_pk_bf16_f32 v6, v24, v25
	v_cvt_pk_bf16_f32 v7, v26, v27
	v_cvt_pk_bf16_f32 v8, v28, v29
	v_cvt_pk_bf16_f32 v9, v30, v31
	global_load_dword v24, v73, s[76:77] offset:-3904
	global_load_dword v25, v73, s[76:77] offset:-1856
	global_load_dword v26, v73, s[76:77] offset:192
	global_load_dword v27, v73, s[76:77] offset:2240
	global_load_dword v28, v73, s[78:79] offset:-3904
	global_load_dword v29, v73, s[78:79] offset:-1856
	global_load_dword v30, v73, s[78:79] offset:192
	global_load_dword v31, v73, s[78:79] offset:2240
	s_add_u32 s76, s76, 0x80000
	s_addc_u32 s77, s77, 0
	s_add_u32 s78, s78, 0x80000
	s_addc_u32 s79, s79, 0
	v_mfma_f32_16x16x32_bf16 v[184:187], v[6:9], v[10:13], v[184:187]
	s_waitcnt vmcnt(40)
	v_cvt_pk_bf16_f32 v2, v32, v33
	v_cvt_pk_bf16_f32 v3, v34, v35
	v_cvt_pk_bf16_f32 v4, v36, v37
	v_cvt_pk_bf16_f32 v5, v38, v39
	global_load_dword v32, v73, s[76:77] offset:-4096
	global_load_dword v33, v73, s[76:77] offset:-2048
	global_load_dword v34, v73, s[76:77] offset:0
	global_load_dword v35, v73, s[76:77] offset:2048
	global_load_dword v36, v73, s[78:79] offset:-4096
	global_load_dword v37, v73, s[78:79] offset:-2048
	global_load_dword v38, v73, s[78:79] offset:0
	global_load_dword v39, v73, s[78:79] offset:2048
	v_mfma_f32_16x16x32_bf16 v[188:191], v[2:5], v[10:13], v[188:191]
	s_waitcnt vmcnt(40)
	v_cvt_pk_bf16_f32 v6, v40, v41
	v_cvt_pk_bf16_f32 v7, v42, v43
	v_cvt_pk_bf16_f32 v8, v44, v45
	v_cvt_pk_bf16_f32 v9, v46, v47
	global_load_dword v40, v73, s[76:77] offset:-4032
	global_load_dword v41, v73, s[76:77] offset:-1984
	global_load_dword v42, v73, s[76:77] offset:64
	global_load_dword v43, v73, s[76:77] offset:2112
	global_load_dword v44, v73, s[78:79] offset:-4032
	global_load_dword v45, v73, s[78:79] offset:-1984
	global_load_dword v46, v73, s[78:79] offset:64
	global_load_dword v47, v73, s[78:79] offset:2112
	v_mfma_f32_16x16x32_bf16 v[192:195], v[6:9], v[10:13], v[192:195]
	v_cvt_pk_bf16_f32 v10, v120, v121
	v_cvt_pk_bf16_f32 v11, v122, v123
	v_cvt_pk_bf16_f32 v12, v124, v125
	v_cvt_pk_bf16_f32 v13, v126, v127
	s_waitcnt vmcnt(40)
	v_cvt_pk_bf16_f32 v2, v48, v49
	v_cvt_pk_bf16_f32 v3, v50, v51
	v_cvt_pk_bf16_f32 v4, v52, v53
	v_cvt_pk_bf16_f32 v5, v54, v55
	global_load_dword v48, v73, s[76:77] offset:-3968
	global_load_dword v49, v73, s[76:77] offset:-1920
	global_load_dword v50, v73, s[76:77] offset:128
	global_load_dword v51, v73, s[76:77] offset:2176
	global_load_dword v52, v73, s[78:79] offset:-3968
	global_load_dword v53, v73, s[78:79] offset:-1920
	global_load_dword v54, v73, s[78:79] offset:128
	global_load_dword v55, v73, s[78:79] offset:2176
	v_mfma_f32_16x16x32_bf16 v[180:183], v[2:5], v[10:13], v[180:183]
	s_waitcnt vmcnt(40)
	v_cvt_pk_bf16_f32 v6, v56, v57
	v_cvt_pk_bf16_f32 v7, v58, v59
	v_cvt_pk_bf16_f32 v8, v60, v61
	v_cvt_pk_bf16_f32 v9, v62, v63
	global_load_dword v56, v73, s[76:77] offset:-3904
	global_load_dword v57, v73, s[76:77] offset:-1856
	global_load_dword v58, v73, s[76:77] offset:192
	global_load_dword v59, v73, s[76:77] offset:2240
	global_load_dword v60, v73, s[78:79] offset:-3904
	global_load_dword v61, v73, s[78:79] offset:-1856
	global_load_dword v62, v73, s[78:79] offset:192
	global_load_dword v63, v73, s[78:79] offset:2240
	s_add_u32 s76, s76, 0x80000
	s_addc_u32 s77, s77, 0
	s_add_u32 s78, s78, 0x80000
	s_addc_u32 s79, s79, 0
	v_mfma_f32_16x16x32_bf16 v[184:187], v[6:9], v[10:13], v[184:187]
	s_waitcnt vmcnt(40)
	v_cvt_pk_bf16_f32 v2, v16, v17
	v_cvt_pk_bf16_f32 v3, v18, v19
	v_cvt_pk_bf16_f32 v4, v20, v21
	v_cvt_pk_bf16_f32 v5, v22, v23
	global_load_dword v16, v73, s[76:77] offset:-4096
	global_load_dword v17, v73, s[76:77] offset:-2048
	global_load_dword v18, v73, s[76:77] offset:0
	global_load_dword v19, v73, s[76:77] offset:2048
	global_load_dword v20, v73, s[78:79] offset:-4096
	global_load_dword v21, v73, s[78:79] offset:-2048
	global_load_dword v22, v73, s[78:79] offset:0
	global_load_dword v23, v73, s[78:79] offset:2048
	v_mfma_f32_16x16x32_bf16 v[188:191], v[2:5], v[10:13], v[188:191]
	s_waitcnt vmcnt(40)
	v_cvt_pk_bf16_f32 v6, v24, v25
	v_cvt_pk_bf16_f32 v7, v26, v27
	v_cvt_pk_bf16_f32 v8, v28, v29
	v_cvt_pk_bf16_f32 v9, v30, v31
	global_load_dword v24, v73, s[76:77] offset:-4032
	global_load_dword v25, v73, s[76:77] offset:-1984
	global_load_dword v26, v73, s[76:77] offset:64
	global_load_dword v27, v73, s[76:77] offset:2112
	global_load_dword v28, v73, s[78:79] offset:-4032
	global_load_dword v29, v73, s[78:79] offset:-1984
	global_load_dword v30, v73, s[78:79] offset:64
	global_load_dword v31, v73, s[78:79] offset:2112
	v_mfma_f32_16x16x32_bf16 v[192:195], v[6:9], v[10:13], v[192:195]
	v_cvt_pk_bf16_f32 v10, v128, v129
	v_cvt_pk_bf16_f32 v11, v130, v131
	v_cvt_pk_bf16_f32 v12, v132, v133
	v_cvt_pk_bf16_f32 v13, v134, v135
	s_waitcnt vmcnt(40)
	v_cvt_pk_bf16_f32 v2, v32, v33
	v_cvt_pk_bf16_f32 v3, v34, v35
	v_cvt_pk_bf16_f32 v4, v36, v37
	v_cvt_pk_bf16_f32 v5, v38, v39
	global_load_dword v32, v73, s[76:77] offset:-3968
	global_load_dword v33, v73, s[76:77] offset:-1920
	global_load_dword v34, v73, s[76:77] offset:128
	global_load_dword v35, v73, s[76:77] offset:2176
	global_load_dword v36, v73, s[78:79] offset:-3968
	global_load_dword v37, v73, s[78:79] offset:-1920
	global_load_dword v38, v73, s[78:79] offset:128
	global_load_dword v39, v73, s[78:79] offset:2176
	v_mfma_f32_16x16x32_bf16 v[180:183], v[2:5], v[10:13], v[180:183]
	s_waitcnt vmcnt(40)
	v_cvt_pk_bf16_f32 v6, v40, v41
	v_cvt_pk_bf16_f32 v7, v42, v43
	v_cvt_pk_bf16_f32 v8, v44, v45
	v_cvt_pk_bf16_f32 v9, v46, v47
	global_load_dword v40, v73, s[76:77] offset:-3904
	global_load_dword v41, v73, s[76:77] offset:-1856
	global_load_dword v42, v73, s[76:77] offset:192
	global_load_dword v43, v73, s[76:77] offset:2240
	global_load_dword v44, v73, s[78:79] offset:-3904
	global_load_dword v45, v73, s[78:79] offset:-1856
	global_load_dword v46, v73, s[78:79] offset:192
	global_load_dword v47, v73, s[78:79] offset:2240
	s_add_u32 s76, s76, 0x80000
	s_addc_u32 s77, s77, 0
	s_add_u32 s78, s78, 0x80000
	s_addc_u32 s79, s79, 0
	v_mfma_f32_16x16x32_bf16 v[184:187], v[6:9], v[10:13], v[184:187]
	s_waitcnt vmcnt(40)
	v_cvt_pk_bf16_f32 v2, v48, v49
	v_cvt_pk_bf16_f32 v3, v50, v51
	v_cvt_pk_bf16_f32 v4, v52, v53
	v_cvt_pk_bf16_f32 v5, v54, v55
	global_load_dword v48, v73, s[76:77] offset:-4096
	global_load_dword v49, v73, s[76:77] offset:-2048
	global_load_dword v50, v73, s[76:77] offset:0
	global_load_dword v51, v73, s[76:77] offset:2048
	global_load_dword v52, v73, s[78:79] offset:-4096
	global_load_dword v53, v73, s[78:79] offset:-2048
	global_load_dword v54, v73, s[78:79] offset:0
	global_load_dword v55, v73, s[78:79] offset:2048
	v_mfma_f32_16x16x32_bf16 v[188:191], v[2:5], v[10:13], v[188:191]
	s_waitcnt vmcnt(40)
	v_cvt_pk_bf16_f32 v6, v56, v57
	v_cvt_pk_bf16_f32 v7, v58, v59
	v_cvt_pk_bf16_f32 v8, v60, v61
	v_cvt_pk_bf16_f32 v9, v62, v63
	global_load_dword v56, v73, s[76:77] offset:-4032
	global_load_dword v57, v73, s[76:77] offset:-1984
	global_load_dword v58, v73, s[76:77] offset:64
	global_load_dword v59, v73, s[76:77] offset:2112
	global_load_dword v60, v73, s[78:79] offset:-4032
	global_load_dword v61, v73, s[78:79] offset:-1984
	global_load_dword v62, v73, s[78:79] offset:64
	global_load_dword v63, v73, s[78:79] offset:2112
	v_mfma_f32_16x16x32_bf16 v[192:195], v[6:9], v[10:13], v[192:195]
	v_cvt_pk_bf16_f32 v10, v136, v137
	v_cvt_pk_bf16_f32 v11, v138, v139
	v_cvt_pk_bf16_f32 v12, v140, v141
	v_cvt_pk_bf16_f32 v13, v142, v143
	s_waitcnt vmcnt(40)
	v_cvt_pk_bf16_f32 v2, v16, v17
	v_cvt_pk_bf16_f32 v3, v18, v19
	v_cvt_pk_bf16_f32 v4, v20, v21
	v_cvt_pk_bf16_f32 v5, v22, v23
	global_load_dword v16, v73, s[76:77] offset:-3968
	global_load_dword v17, v73, s[76:77] offset:-1920
	global_load_dword v18, v73, s[76:77] offset:128
	global_load_dword v19, v73, s[76:77] offset:2176
	global_load_dword v20, v73, s[78:79] offset:-3968
	global_load_dword v21, v73, s[78:79] offset:-1920
	global_load_dword v22, v73, s[78:79] offset:128
	global_load_dword v23, v73, s[78:79] offset:2176
	v_mfma_f32_16x16x32_bf16 v[180:183], v[2:5], v[10:13], v[180:183]
	s_waitcnt vmcnt(40)
	v_cvt_pk_bf16_f32 v6, v24, v25
	v_cvt_pk_bf16_f32 v7, v26, v27
	v_cvt_pk_bf16_f32 v8, v28, v29
	v_cvt_pk_bf16_f32 v9, v30, v31
	global_load_dword v24, v73, s[76:77] offset:-3904
	global_load_dword v25, v73, s[76:77] offset:-1856
	global_load_dword v26, v73, s[76:77] offset:192
	global_load_dword v27, v73, s[76:77] offset:2240
	global_load_dword v28, v73, s[78:79] offset:-3904
	global_load_dword v29, v73, s[78:79] offset:-1856
	global_load_dword v30, v73, s[78:79] offset:192
	global_load_dword v31, v73, s[78:79] offset:2240
	s_add_u32 s76, s76, 0x80000
	s_addc_u32 s77, s77, 0
	s_add_u32 s78, s78, 0x80000
	s_addc_u32 s79, s79, 0
	v_mfma_f32_16x16x32_bf16 v[184:187], v[6:9], v[10:13], v[184:187]
	s_waitcnt vmcnt(40)
	v_cvt_pk_bf16_f32 v2, v32, v33
	v_cvt_pk_bf16_f32 v3, v34, v35
	v_cvt_pk_bf16_f32 v4, v36, v37
	v_cvt_pk_bf16_f32 v5, v38, v39
	global_load_dword v32, v73, s[76:77] offset:-4096
	global_load_dword v33, v73, s[76:77] offset:-2048
	global_load_dword v34, v73, s[76:77] offset:0
	global_load_dword v35, v73, s[76:77] offset:2048
	global_load_dword v36, v73, s[78:79] offset:-4096
	global_load_dword v37, v73, s[78:79] offset:-2048
	global_load_dword v38, v73, s[78:79] offset:0
	global_load_dword v39, v73, s[78:79] offset:2048
	v_mfma_f32_16x16x32_bf16 v[188:191], v[2:5], v[10:13], v[188:191]
	s_waitcnt vmcnt(40)
	v_cvt_pk_bf16_f32 v6, v40, v41
	v_cvt_pk_bf16_f32 v7, v42, v43
	v_cvt_pk_bf16_f32 v8, v44, v45
	v_cvt_pk_bf16_f32 v9, v46, v47
	global_load_dword v40, v73, s[76:77] offset:-4032
	global_load_dword v41, v73, s[76:77] offset:-1984
	global_load_dword v42, v73, s[76:77] offset:64
	global_load_dword v43, v73, s[76:77] offset:2112
	global_load_dword v44, v73, s[78:79] offset:-4032
	global_load_dword v45, v73, s[78:79] offset:-1984
	global_load_dword v46, v73, s[78:79] offset:64
	global_load_dword v47, v73, s[78:79] offset:2112
	v_mfma_f32_16x16x32_bf16 v[192:195], v[6:9], v[10:13], v[192:195]
	v_cvt_pk_bf16_f32 v10, v144, v145
	v_cvt_pk_bf16_f32 v11, v146, v147
	v_cvt_pk_bf16_f32 v12, v148, v149
	v_cvt_pk_bf16_f32 v13, v150, v151
	s_waitcnt vmcnt(40)
	v_cvt_pk_bf16_f32 v2, v48, v49
	v_cvt_pk_bf16_f32 v3, v50, v51
	v_cvt_pk_bf16_f32 v4, v52, v53
	v_cvt_pk_bf16_f32 v5, v54, v55
	global_load_dword v48, v73, s[76:77] offset:-3968
	global_load_dword v49, v73, s[76:77] offset:-1920
	global_load_dword v50, v73, s[76:77] offset:128
	global_load_dword v51, v73, s[76:77] offset:2176
	global_load_dword v52, v73, s[78:79] offset:-3968
	global_load_dword v53, v73, s[78:79] offset:-1920
	global_load_dword v54, v73, s[78:79] offset:128
	global_load_dword v55, v73, s[78:79] offset:2176
	v_mfma_f32_16x16x32_bf16 v[180:183], v[2:5], v[10:13], v[180:183]
	s_waitcnt vmcnt(40)
	v_cvt_pk_bf16_f32 v6, v56, v57
	v_cvt_pk_bf16_f32 v7, v58, v59
	v_cvt_pk_bf16_f32 v8, v60, v61
	v_cvt_pk_bf16_f32 v9, v62, v63
	global_load_dword v56, v73, s[76:77] offset:-3904
	global_load_dword v57, v73, s[76:77] offset:-1856
	global_load_dword v58, v73, s[76:77] offset:192
	global_load_dword v59, v73, s[76:77] offset:2240
	global_load_dword v60, v73, s[78:79] offset:-3904
	global_load_dword v61, v73, s[78:79] offset:-1856
	global_load_dword v62, v73, s[78:79] offset:192
	global_load_dword v63, v73, s[78:79] offset:2240
	s_add_u32 s76, s76, 0x80000
	s_addc_u32 s77, s77, 0
	s_add_u32 s78, s78, 0x80000
	s_addc_u32 s79, s79, 0
	v_mfma_f32_16x16x32_bf16 v[184:187], v[6:9], v[10:13], v[184:187]
	s_waitcnt vmcnt(40)
	v_cvt_pk_bf16_f32 v2, v16, v17
	v_cvt_pk_bf16_f32 v3, v18, v19
	v_cvt_pk_bf16_f32 v4, v20, v21
	v_cvt_pk_bf16_f32 v5, v22, v23
	global_load_dword v16, v73, s[76:77] offset:-4096
	global_load_dword v17, v73, s[76:77] offset:-2048
	global_load_dword v18, v73, s[76:77] offset:0
	global_load_dword v19, v73, s[76:77] offset:2048
	global_load_dword v20, v73, s[78:79] offset:-4096
	global_load_dword v21, v73, s[78:79] offset:-2048
	global_load_dword v22, v73, s[78:79] offset:0
	global_load_dword v23, v73, s[78:79] offset:2048
	v_mfma_f32_16x16x32_bf16 v[188:191], v[2:5], v[10:13], v[188:191]
	s_waitcnt vmcnt(40)
	v_cvt_pk_bf16_f32 v6, v24, v25
	v_cvt_pk_bf16_f32 v7, v26, v27
	v_cvt_pk_bf16_f32 v8, v28, v29
	v_cvt_pk_bf16_f32 v9, v30, v31
	global_load_dword v24, v73, s[76:77] offset:-4032
	global_load_dword v25, v73, s[76:77] offset:-1984
	global_load_dword v26, v73, s[76:77] offset:64
	global_load_dword v27, v73, s[76:77] offset:2112
	global_load_dword v28, v73, s[78:79] offset:-4032
	global_load_dword v29, v73, s[78:79] offset:-1984
	global_load_dword v30, v73, s[78:79] offset:64
	global_load_dword v31, v73, s[78:79] offset:2112
	v_mfma_f32_16x16x32_bf16 v[192:195], v[6:9], v[10:13], v[192:195]
	v_cvt_pk_bf16_f32 v10, v152, v153
	v_cvt_pk_bf16_f32 v11, v154, v155
	v_cvt_pk_bf16_f32 v12, v156, v157
	v_cvt_pk_bf16_f32 v13, v158, v159
	s_waitcnt vmcnt(40)
	v_cvt_pk_bf16_f32 v2, v32, v33
	v_cvt_pk_bf16_f32 v3, v34, v35
	v_cvt_pk_bf16_f32 v4, v36, v37
	v_cvt_pk_bf16_f32 v5, v38, v39
	global_load_dword v32, v73, s[76:77] offset:-3968
	global_load_dword v33, v73, s[76:77] offset:-1920
	global_load_dword v34, v73, s[76:77] offset:128
	global_load_dword v35, v73, s[76:77] offset:2176
	global_load_dword v36, v73, s[78:79] offset:-3968
	global_load_dword v37, v73, s[78:79] offset:-1920
	global_load_dword v38, v73, s[78:79] offset:128
	global_load_dword v39, v73, s[78:79] offset:2176
	v_mfma_f32_16x16x32_bf16 v[180:183], v[2:5], v[10:13], v[180:183]
	s_waitcnt vmcnt(40)
	v_cvt_pk_bf16_f32 v6, v40, v41
	v_cvt_pk_bf16_f32 v7, v42, v43
	v_cvt_pk_bf16_f32 v8, v44, v45
	v_cvt_pk_bf16_f32 v9, v46, v47
	global_load_dword v40, v73, s[76:77] offset:-3904
	global_load_dword v41, v73, s[76:77] offset:-1856
	global_load_dword v42, v73, s[76:77] offset:192
	global_load_dword v43, v73, s[76:77] offset:2240
	global_load_dword v44, v73, s[78:79] offset:-3904
	global_load_dword v45, v73, s[78:79] offset:-1856
	global_load_dword v46, v73, s[78:79] offset:192
	global_load_dword v47, v73, s[78:79] offset:2240
	s_add_u32 s76, s76, 0x80000
	s_addc_u32 s77, s77, 0
	s_add_u32 s78, s78, 0x80000
	s_addc_u32 s79, s79, 0
	v_mfma_f32_16x16x32_bf16 v[184:187], v[6:9], v[10:13], v[184:187]
	s_waitcnt vmcnt(40)
	v_cvt_pk_bf16_f32 v2, v48, v49
	v_cvt_pk_bf16_f32 v3, v50, v51
	v_cvt_pk_bf16_f32 v4, v52, v53
	v_cvt_pk_bf16_f32 v5, v54, v55
	global_load_dword v48, v73, s[76:77] offset:-4096
	global_load_dword v49, v73, s[76:77] offset:-2048
	global_load_dword v50, v73, s[76:77] offset:0
	global_load_dword v51, v73, s[76:77] offset:2048
	global_load_dword v52, v73, s[78:79] offset:-4096
	global_load_dword v53, v73, s[78:79] offset:-2048
	global_load_dword v54, v73, s[78:79] offset:0
	global_load_dword v55, v73, s[78:79] offset:2048
	v_mfma_f32_16x16x32_bf16 v[188:191], v[2:5], v[10:13], v[188:191]
	s_waitcnt vmcnt(40)
	v_cvt_pk_bf16_f32 v6, v56, v57
	v_cvt_pk_bf16_f32 v7, v58, v59
	v_cvt_pk_bf16_f32 v8, v60, v61
	v_cvt_pk_bf16_f32 v9, v62, v63
	global_load_dword v56, v73, s[76:77] offset:-4032
	global_load_dword v57, v73, s[76:77] offset:-1984
	global_load_dword v58, v73, s[76:77] offset:64
	global_load_dword v59, v73, s[76:77] offset:2112
	global_load_dword v60, v73, s[78:79] offset:-4032
	global_load_dword v61, v73, s[78:79] offset:-1984
	global_load_dword v62, v73, s[78:79] offset:64
	global_load_dword v63, v73, s[78:79] offset:2112
	v_mfma_f32_16x16x32_bf16 v[192:195], v[6:9], v[10:13], v[192:195]
	v_cvt_pk_bf16_f32 v10, v160, v161
	v_cvt_pk_bf16_f32 v11, v162, v163
	v_cvt_pk_bf16_f32 v12, v164, v165
	v_cvt_pk_bf16_f32 v13, v166, v167
	s_waitcnt vmcnt(40)
	v_cvt_pk_bf16_f32 v2, v16, v17
	v_cvt_pk_bf16_f32 v3, v18, v19
	v_cvt_pk_bf16_f32 v4, v20, v21
	v_cvt_pk_bf16_f32 v5, v22, v23
	global_load_dword v16, v73, s[76:77] offset:-3968
	global_load_dword v17, v73, s[76:77] offset:-1920
	global_load_dword v18, v73, s[76:77] offset:128
	global_load_dword v19, v73, s[76:77] offset:2176
	global_load_dword v20, v73, s[78:79] offset:-3968
	global_load_dword v21, v73, s[78:79] offset:-1920
	global_load_dword v22, v73, s[78:79] offset:128
	global_load_dword v23, v73, s[78:79] offset:2176
	v_mfma_f32_16x16x32_bf16 v[180:183], v[2:5], v[10:13], v[180:183]
	s_waitcnt vmcnt(40)
	v_cvt_pk_bf16_f32 v6, v24, v25
	v_cvt_pk_bf16_f32 v7, v26, v27
	v_cvt_pk_bf16_f32 v8, v28, v29
	v_cvt_pk_bf16_f32 v9, v30, v31
	global_load_dword v24, v73, s[76:77] offset:-3904
	global_load_dword v25, v73, s[76:77] offset:-1856
	global_load_dword v26, v73, s[76:77] offset:192
	global_load_dword v27, v73, s[76:77] offset:2240
	global_load_dword v28, v73, s[78:79] offset:-3904
	global_load_dword v29, v73, s[78:79] offset:-1856
	global_load_dword v30, v73, s[78:79] offset:192
	global_load_dword v31, v73, s[78:79] offset:2240
	s_add_u32 s76, s76, 0x80000
	s_addc_u32 s77, s77, 0
	s_add_u32 s78, s78, 0x80000
	s_addc_u32 s79, s79, 0
	v_mfma_f32_16x16x32_bf16 v[184:187], v[6:9], v[10:13], v[184:187]
	s_waitcnt vmcnt(40)
	v_cvt_pk_bf16_f32 v2, v32, v33
	v_cvt_pk_bf16_f32 v3, v34, v35
	v_cvt_pk_bf16_f32 v4, v36, v37
	v_cvt_pk_bf16_f32 v5, v38, v39
	s_nop 1
	v_mfma_f32_16x16x32_bf16 v[188:191], v[2:5], v[10:13], v[188:191]
	s_waitcnt vmcnt(32)
	v_cvt_pk_bf16_f32 v6, v40, v41
	v_cvt_pk_bf16_f32 v7, v42, v43
	v_cvt_pk_bf16_f32 v8, v44, v45
	v_cvt_pk_bf16_f32 v9, v46, v47
	s_nop 1
	v_mfma_f32_16x16x32_bf16 v[192:195], v[6:9], v[10:13], v[192:195]
	v_cvt_pk_bf16_f32 v10, v168, v169
	v_cvt_pk_bf16_f32 v11, v170, v171
	v_cvt_pk_bf16_f32 v12, v172, v173
	v_cvt_pk_bf16_f32 v13, v174, v175
	s_waitcnt vmcnt(24)
	v_cvt_pk_bf16_f32 v2, v48, v49
	v_cvt_pk_bf16_f32 v3, v50, v51
	v_cvt_pk_bf16_f32 v4, v52, v53
	v_cvt_pk_bf16_f32 v5, v54, v55
	s_nop 1
	v_mfma_f32_16x16x32_bf16 v[180:183], v[2:5], v[10:13], v[180:183]
	s_waitcnt vmcnt(16)
	v_cvt_pk_bf16_f32 v6, v56, v57
	v_cvt_pk_bf16_f32 v7, v58, v59
	v_cvt_pk_bf16_f32 v8, v60, v61
	v_cvt_pk_bf16_f32 v9, v62, v63
	s_nop 1
	v_mfma_f32_16x16x32_bf16 v[184:187], v[6:9], v[10:13], v[184:187]
	s_waitcnt vmcnt(8)
	v_cvt_pk_bf16_f32 v2, v16, v17
	v_cvt_pk_bf16_f32 v3, v18, v19
	v_cvt_pk_bf16_f32 v4, v20, v21
	v_cvt_pk_bf16_f32 v5, v22, v23
	s_nop 1
	v_mfma_f32_16x16x32_bf16 v[188:191], v[2:5], v[10:13], v[188:191]
	s_waitcnt vmcnt(0)
	v_cvt_pk_bf16_f32 v6, v24, v25
	v_cvt_pk_bf16_f32 v7, v26, v27
	v_cvt_pk_bf16_f32 v8, v28, v29
	v_cvt_pk_bf16_f32 v9, v30, v31
	s_nop 1
	v_mfma_f32_16x16x32_bf16 v[192:195], v[6:9], v[10:13], v[192:195]
	s_cmp_lg_u32 s72, 0
	s_cbranch_scc1 .Lsa_pv16_skip
	v_cvt_pk_bf16_f32 v10, v176, v177
	v_cvt_pk_bf16_f32 v11, v178, v179
	v_mov_b32_e32 v12, 0
	v_mov_b32_e32 v13, 0
	v_mov_b32_e32 v4, 0
	v_mov_b32_e32 v5, 0
	v_mov_b32_e32 v8, 0
	v_mov_b32_e32 v9, 0
	v_cvt_pk_bf16_f32 v2, v232, v233
	v_cvt_pk_bf16_f32 v3, v234, v235
	s_nop 1
	v_mfma_f32_16x16x32_bf16 v[180:183], v[2:5], v[10:13], v[180:183]
	v_cvt_pk_bf16_f32 v6, v236, v237
	v_cvt_pk_bf16_f32 v7, v238, v239
	s_nop 1
	v_mfma_f32_16x16x32_bf16 v[184:187], v[6:9], v[10:13], v[184:187]
	v_cvt_pk_bf16_f32 v2, v240, v241
	v_cvt_pk_bf16_f32 v3, v242, v243
	s_nop 1
	v_mfma_f32_16x16x32_bf16 v[188:191], v[2:5], v[10:13], v[188:191]
	v_cvt_pk_bf16_f32 v6, v244, v245
	v_cvt_pk_bf16_f32 v7, v246, v247
	s_nop 1
	v_mfma_f32_16x16x32_bf16 v[192:195], v[6:9], v[10:13], v[192:195]
.Lsa_pv16_skip:
	v_lshlrev_b32_e32 v105, 8, v77
	v_lshl_add_u32 v105, v75, 4, v105
	s_lshl_b32 s0, s72, 12
	s_add_i32 s0, s0, 0x4010
	v_add_u32_e32 v105, s0, v105
	s_nop 7
	s_nop 1
	ds_write_b128 v105, v[180:183]
	ds_write_b128 v105, v[184:187] offset:64
	ds_write_b128 v105, v[188:191] offset:128
	ds_write_b128 v105, v[192:195] offset:192
	v_and_b32_e32 v106, 63, v0
	v_lshlrev_b32_e32 v106, 2, v106
	v_lshrrev_b32_e32 v111, 1, v106
	s_waitcnt lgkmcnt(0)
	s_barrier
	s_add_i32 s0, s72, 0
	s_lshl_b32 s1, s0, 8
	s_add_i32 s1, s1, 0x4010
	v_add_u32_e32 v107, s1, v106
	ds_read_b32 v200, v107
	ds_read_b32 v201, v107 offset:4096
	ds_read_b32 v202, v107 offset:8192
	ds_read_b32 v203, v107 offset:12288
	ds_read_b32 v204, v107 offset:16384
	ds_read_b32 v205, v107 offset:20480
	ds_read_b32 v206, v107 offset:24576
	ds_read_b32 v207, v107 offset:28672
	s_lshl_b32 s1, s0, 2
	s_add_i32 s1, s1, 0xc810
	v_mov_b32_e32 v108, s1
	v_add_u32_e32 v109, 64, v108
	v_add_u32_e32 v110, 0x80, v108
	v_add_u32_e32 v105, 0xc0, v108
	ds_read2st64_b32 v[208:209], v108 offset0:0 offset1:1
	ds_read2st64_b32 v[210:211], v108 offset0:2 offset1:3
	ds_read2st64_b32 v[212:213], v108 offset0:4 offset1:5
	ds_read2st64_b32 v[214:215], v108 offset0:6 offset1:7
	ds_read2st64_b32 v[216:217], v109 offset0:0 offset1:1
	ds_read2st64_b32 v[218:219], v109 offset0:2 offset1:3
	ds_read2st64_b32 v[220:221], v109 offset0:4 offset1:5
	ds_read2st64_b32 v[222:223], v109 offset0:6 offset1:7
	ds_read2st64_b32 v[224:225], v110 offset0:0 offset1:1
	ds_read2st64_b32 v[226:227], v110 offset0:2 offset1:3
	ds_read2st64_b32 v[228:229], v110 offset0:4 offset1:5
	ds_read2st64_b32 v[230:231], v110 offset0:6 offset1:7
	ds_read2st64_b32 v[232:233], v105 offset0:0 offset1:1
	ds_read2st64_b32 v[234:235], v105 offset0:2 offset1:3
	ds_read2st64_b32 v[236:237], v105 offset0:4 offset1:5
	ds_read2st64_b32 v[238:239], v105 offset0:6 offset1:7
	s_waitcnt lgkmcnt(0)
	v_add_f32_e32 v200, v200, v201
	v_add_f32_e32 v200, v200, v202
	v_add_f32_e32 v200, v200, v203
	v_add_f32_e32 v200, v200, v204
	v_add_f32_e32 v200, v200, v205
	v_add_f32_e32 v200, v200, v206
	v_add_f32_e32 v200, v200, v207
	v_add_f32_e32 v208, v208, v209
	v_add_f32_e32 v208, v208, v210
	v_add_f32_e32 v208, v208, v211
	v_add_f32_e32 v208, v208, v212
	v_add_f32_e32 v208, v208, v213
	v_add_f32_e32 v208, v208, v214
	v_add_f32_e32 v208, v208, v215
	v_add_f32_e32 v208, v208, v216
	v_add_f32_e32 v208, v208, v217
	v_add_f32_e32 v208, v208, v218
	v_add_f32_e32 v208, v208, v219
	v_add_f32_e32 v208, v208, v220
	v_add_f32_e32 v208, v208, v221
	v_add_f32_e32 v208, v208, v222
	v_add_f32_e32 v208, v208, v223
	v_add_f32_e32 v208, v208, v224
	v_add_f32_e32 v208, v208, v225
	v_add_f32_e32 v208, v208, v226
	v_add_f32_e32 v208, v208, v227
	v_add_f32_e32 v208, v208, v228
	v_add_f32_e32 v208, v208, v229
	v_add_f32_e32 v208, v208, v230
	v_add_f32_e32 v208, v208, v231
	v_add_f32_e32 v208, v208, v232
	v_add_f32_e32 v208, v208, v233
	v_add_f32_e32 v208, v208, v234
	v_add_f32_e32 v208, v208, v235
	v_add_f32_e32 v208, v208, v236
	v_add_f32_e32 v208, v208, v237
	v_add_f32_e32 v208, v208, v238
	v_add_f32_e32 v208, v208, v239
	v_div_scale_f32 v2, s[4:5], v208, v208, v200
	v_rcp_f32_e32 v3, v2
	s_nop 0
	v_fma_f32 v4, -v2, v3, 1.0
	v_fmac_f32_e32 v3, v4, v3
	v_div_scale_f32 v4, vcc, v200, v208, v200
	v_mul_f32_e32 v5, v4, v3
	v_fma_f32 v6, -v2, v5, v4
	v_fmac_f32_e32 v5, v6, v3
	v_fma_f32 v2, -v2, v5, v4
	v_div_fmas_f32 v2, v2, v3, v5
	v_div_fixup_f32 v2, v2, v208, v200
	v_cvt_pk_bf16_f32 v2, v2, v79
	s_lshl_b32 s1, s0, 10
	s_add_u32 s2, s86, s1
	s_addc_u32 s3, s87, 0
	global_store_short v111, v2, s[2:3]
	s_add_i32 s0, s72, 8
	s_lshl_b32 s1, s0, 8
	s_add_i32 s1, s1, 0x4010
	v_add_u32_e32 v107, s1, v106
	ds_read_b32 v200, v107
	ds_read_b32 v201, v107 offset:4096
	ds_read_b32 v202, v107 offset:8192
	ds_read_b32 v203, v107 offset:12288
	ds_read_b32 v204, v107 offset:16384
	ds_read_b32 v205, v107 offset:20480
	ds_read_b32 v206, v107 offset:24576
	ds_read_b32 v207, v107 offset:28672
	s_lshl_b32 s1, s0, 2
	s_add_i32 s1, s1, 0xc810
	v_mov_b32_e32 v108, s1
	v_add_u32_e32 v109, 64, v108
	v_add_u32_e32 v110, 0x80, v108
	v_add_u32_e32 v105, 0xc0, v108
	ds_read2st64_b32 v[208:209], v108 offset0:0 offset1:1
	ds_read2st64_b32 v[210:211], v108 offset0:2 offset1:3
	ds_read2st64_b32 v[212:213], v108 offset0:4 offset1:5
	ds_read2st64_b32 v[214:215], v108 offset0:6 offset1:7
	ds_read2st64_b32 v[216:217], v109 offset0:0 offset1:1
	ds_read2st64_b32 v[218:219], v109 offset0:2 offset1:3
	ds_read2st64_b32 v[220:221], v109 offset0:4 offset1:5
	ds_read2st64_b32 v[222:223], v109 offset0:6 offset1:7
	ds_read2st64_b32 v[224:225], v110 offset0:0 offset1:1
	ds_read2st64_b32 v[226:227], v110 offset0:2 offset1:3
	ds_read2st64_b32 v[228:229], v110 offset0:4 offset1:5
	ds_read2st64_b32 v[230:231], v110 offset0:6 offset1:7
	ds_read2st64_b32 v[232:233], v105 offset0:0 offset1:1
	ds_read2st64_b32 v[234:235], v105 offset0:2 offset1:3
	ds_read2st64_b32 v[236:237], v105 offset0:4 offset1:5
	ds_read2st64_b32 v[238:239], v105 offset0:6 offset1:7
	s_waitcnt lgkmcnt(0)
	v_add_f32_e32 v200, v200, v201
	v_add_f32_e32 v200, v200, v202
	v_add_f32_e32 v200, v200, v203
	v_add_f32_e32 v200, v200, v204
	v_add_f32_e32 v200, v200, v205
	v_add_f32_e32 v200, v200, v206
	v_add_f32_e32 v200, v200, v207
	v_add_f32_e32 v208, v208, v209
	v_add_f32_e32 v208, v208, v210
	v_add_f32_e32 v208, v208, v211
	v_add_f32_e32 v208, v208, v212
	v_add_f32_e32 v208, v208, v213
	v_add_f32_e32 v208, v208, v214
	v_add_f32_e32 v208, v208, v215
	v_add_f32_e32 v208, v208, v216
	v_add_f32_e32 v208, v208, v217
	v_add_f32_e32 v208, v208, v218
	v_add_f32_e32 v208, v208, v219
	v_add_f32_e32 v208, v208, v220
	v_add_f32_e32 v208, v208, v221
	v_add_f32_e32 v208, v208, v222
	v_add_f32_e32 v208, v208, v223
	v_add_f32_e32 v208, v208, v224
	v_add_f32_e32 v208, v208, v225
	v_add_f32_e32 v208, v208, v226
	v_add_f32_e32 v208, v208, v227
	v_add_f32_e32 v208, v208, v228
	v_add_f32_e32 v208, v208, v229
	v_add_f32_e32 v208, v208, v230
	v_add_f32_e32 v208, v208, v231
	v_add_f32_e32 v208, v208, v232
	v_add_f32_e32 v208, v208, v233
	v_add_f32_e32 v208, v208, v234
	v_add_f32_e32 v208, v208, v235
	v_add_f32_e32 v208, v208, v236
	v_add_f32_e32 v208, v208, v237
	v_add_f32_e32 v208, v208, v238
	v_add_f32_e32 v208, v208, v239
	v_div_scale_f32 v2, s[4:5], v208, v208, v200
	v_rcp_f32_e32 v3, v2
	s_nop 0
	v_fma_f32 v4, -v2, v3, 1.0
	v_fmac_f32_e32 v3, v4, v3
	v_div_scale_f32 v4, vcc, v200, v208, v200
	v_mul_f32_e32 v5, v4, v3
	v_fma_f32 v6, -v2, v5, v4
	v_fmac_f32_e32 v5, v6, v3
	v_fma_f32 v2, -v2, v5, v4
	v_div_fmas_f32 v2, v2, v3, v5
	v_div_fixup_f32 v2, v2, v208, v200
	v_cvt_pk_bf16_f32 v2, v2, v79
	s_lshl_b32 s1, s0, 10
	s_add_u32 s2, s86, s1
	s_addc_u32 s3, s87, 0
	global_store_short v111, v2, s[2:3]
	v_readlane_b32 s22, v255, 3
	s_branch .LBB0_1797

.LBB0_1490:
	s_or_b64 exec, exec, s[6:7]
	s_and_b64 s[0:1], s[0:1], exec
	v_readlane_b32 s0, v254, 61
	s_cselect_b32 s92, s14, s15
	s_cselect_b32 s2, s0, s89
	v_readlane_b32 s0, v254, 60
	s_cselect_b32 s3, s0, s88
	s_lshl_b64 s[0:1], s[92:93], 18
	s_add_u32 s0, s3, s0
	s_addc_u32 s1, s2, s1
	v_lshlrev_b64 v[2:3], 15, v[46:47]
	v_lshl_add_u64 v[2:3], s[0:1], 0, v[2:3]
	v_readlane_b32 s0, v255, 1
	v_lshl_or_b32 v60, v54, 6, v53
	s_movk_i32 s2, 0x90
	v_lshl_add_u32 v4, v55, 1, s0
	v_lshlrev_b32_e32 v5, 1, v58
	v_mad_u32_u24 v10, v60, s2, v52
	v_add3_u32 v50, v4, v5, v59
	ds_read_b128 v[26:29], v10 offset:38912
	ds_read_b128 v[30:33], v50
	v_lshlrev_b32_e32 v78, 2, v56
	v_lshl_add_u64 v[2:3], v[2:3], 0, v[78:79]
	v_lshlrev_b32_e32 v78, 8, v54
	v_lshl_add_u64 v[40:41], v[2:3], 0, v[78:79]
	ds_read_b128 v[42:45], v10 offset:38976
	ds_read_b128 v[2:5], v50 offset:64
	s_waitcnt lgkmcnt(2)
	v_mfma_f32_16x16x32_bf16 v[6:9], v[26:29], v[30:33], 0
	ds_read_b128 v[18:21], v50 offset:2304
	ds_read_b128 v[10:13], v50 offset:2368
	v_lshlrev_b32_e32 v78, 9, v53
	s_waitcnt lgkmcnt(2)
	v_mfma_f32_16x16x32_bf16 v[6:9], v[42:45], v[2:5], v[6:9]
	v_lshl_add_u64 v[34:35], v[40:41], 0, v[78:79]
	ds_read_b128 v[22:25], v50 offset:4608
	v_or_b32_e32 v38, 0x2000, v78
	v_mov_b32_e32 v39, v79
	v_lshl_add_u64 v[14:15], v[40:41], 0, v[38:39]
	s_nop 2
	global_store_dwordx4 v[34:35], v[6:9], off
	v_or_b32_e32 v36, 0x4000, v78
	v_mov_b32_e32 v37, v79
	s_waitcnt lgkmcnt(2)
	v_mfma_f32_16x16x32_bf16 v[6:9], v[26:29], v[18:21], 0
	v_lshl_add_u64 v[46:47], v[40:41], 0, v[36:37]
	v_or_b32_e32 v78, 0x6000, v78
	s_mov_b64 s[0:1], 0x80
	s_waitcnt lgkmcnt(1)
	v_mfma_f32_16x16x32_bf16 v[6:9], v[42:45], v[10:13], v[6:9]
	s_nop 7
	global_store_dwordx4 v[14:15], v[6:9], off
	ds_read_b128 v[6:9], v50 offset:4672
	s_waitcnt lgkmcnt(1)
	v_mfma_f32_16x16x32_bf16 v[14:17], v[26:29], v[22:25], 0
	s_waitcnt lgkmcnt(0)
	v_mfma_f32_16x16x32_bf16 v[14:17], v[42:45], v[6:9], v[14:17]
	s_nop 7
	global_store_dwordx4 v[46:47], v[14:17], off
	ds_read_b128 v[14:17], v50 offset:6912
	s_waitcnt lgkmcnt(0)
	v_mfma_f32_16x16x32_bf16 v[46:49], v[26:29], v[14:17], 0
	ds_read_b128 v[26:29], v50 offset:6976
	v_lshl_add_u64 v[50:51], v[40:41], 0, 64
	v_lshl_add_u64 v[58:59], v[50:51], 0, v[38:39]
	s_waitcnt lgkmcnt(0)
	v_mfma_f32_16x16x32_bf16 v[42:45], v[42:45], v[26:29], v[46:49]
	s_nop 2
	v_lshl_add_u64 v[46:47], v[40:41], 0, v[78:79]
	s_nop 3
	global_store_dwordx4 v[46:47], v[42:45], off
	s_nop 1
	v_or_b32_e32 v42, 16, v60
	v_mad_u32_u24 v53, v42, s2, v52
	ds_read_b128 v[42:45], v53 offset:38912
	s_waitcnt vmcnt(4)
	ds_read_b128 v[54:57], v53 offset:38976
	s_waitcnt lgkmcnt(1)
	v_mfma_f32_16x16x32_bf16 v[46:49], v[42:45], v[30:33], 0
	s_waitcnt lgkmcnt(0)
	v_mfma_f32_16x16x32_bf16 v[46:49], v[54:57], v[2:5], v[46:49]
	s_nop 7
	global_store_dwordx4 v[34:35], v[46:49], off offset:64
	s_nop 1
	v_mfma_f32_16x16x32_bf16 v[46:49], v[42:45], v[18:21], 0
	v_mfma_f32_16x16x32_bf16 v[46:49], v[54:57], v[10:13], v[46:49]
	s_nop 7
	global_store_dwordx4 v[58:59], v[46:49], off
	v_lshl_add_u64 v[58:59], v[50:51], 0, v[36:37]
	s_nop 0
	v_mfma_f32_16x16x32_bf16 v[46:49], v[42:45], v[22:25], 0
	v_mfma_f32_16x16x32_bf16 v[42:45], v[42:45], v[14:17], 0
	v_mfma_f32_16x16x32_bf16 v[46:49], v[54:57], v[6:9], v[46:49]
	v_mfma_f32_16x16x32_bf16 v[42:45], v[54:57], v[26:29], v[42:45]
	s_nop 6
	global_store_dwordx4 v[58:59], v[46:49], off
	s_nop 1
	v_lshl_add_u64 v[46:47], v[50:51], 0, v[78:79]
	global_store_dwordx4 v[46:47], v[42:45], off
	v_lshl_add_u64 v[50:51], v[40:41], 0, s[0:1]
	v_lshl_add_u64 v[58:59], v[50:51], 0, v[38:39]
	v_or_b32_e32 v42, 32, v60
	v_mad_u32_u24 v53, v42, s2, v52
	ds_read_b128 v[42:45], v53 offset:38912
	ds_read_b128 v[54:57], v53 offset:38976
	s_waitcnt lgkmcnt(1)
	v_mfma_f32_16x16x32_bf16 v[46:49], v[42:45], v[30:33], 0
	s_mov_b64 s[0:1], 0xc0
	s_waitcnt lgkmcnt(0)
	v_mfma_f32_16x16x32_bf16 v[46:49], v[54:57], v[2:5], v[46:49]
	s_nop 7
	global_store_dwordx4 v[34:35], v[46:49], off offset:128
	s_nop 1
	v_mfma_f32_16x16x32_bf16 v[46:49], v[42:45], v[18:21], 0
	v_mfma_f32_16x16x32_bf16 v[46:49], v[54:57], v[10:13], v[46:49]
	s_nop 7
	global_store_dwordx4 v[58:59], v[46:49], off
	v_lshl_add_u64 v[58:59], v[50:51], 0, v[36:37]
	s_nop 0
	v_mfma_f32_16x16x32_bf16 v[46:49], v[42:45], v[22:25], 0
	v_mfma_f32_16x16x32_bf16 v[42:45], v[42:45], v[14:17], 0
	v_mfma_f32_16x16x32_bf16 v[46:49], v[54:57], v[6:9], v[46:49]
	v_mfma_f32_16x16x32_bf16 v[42:45], v[54:57], v[26:29], v[42:45]
	s_nop 6
	global_store_dwordx4 v[58:59], v[46:49], off
	s_nop 1
	v_lshl_add_u64 v[46:47], v[50:51], 0, v[78:79]
	global_store_dwordx4 v[46:47], v[42:45], off
	v_lshl_add_u64 v[48:49], v[40:41], 0, s[0:1]
	s_nop 0
	v_or_b32_e32 v42, 48, v60
	v_mad_u32_u24 v44, v42, s2, v52
	ds_read_b128 v[40:43], v44 offset:38912
	ds_read_b128 v[44:47], v44 offset:38976
	s_waitcnt lgkmcnt(1)
	v_mfma_f32_16x16x32_bf16 v[30:33], v[40:43], v[30:33], 0
	s_waitcnt lgkmcnt(0)
	v_mfma_f32_16x16x32_bf16 v[2:5], v[44:47], v[2:5], v[30:33]
	s_nop 7
	global_store_dwordx4 v[34:35], v[2:5], off offset:192
	s_nop 1
	v_mfma_f32_16x16x32_bf16 v[2:5], v[40:43], v[18:21], 0
	v_mfma_f32_16x16x32_bf16 v[2:5], v[44:47], v[10:13], v[2:5]
	v_lshl_add_u64 v[10:11], v[48:49], 0, v[38:39]
	s_nop 6
	global_store_dwordx4 v[10:11], v[2:5], off
	s_nop 1
	v_mfma_f32_16x16x32_bf16 v[2:5], v[40:43], v[22:25], 0
	v_mfma_f32_16x16x32_bf16 v[2:5], v[44:47], v[6:9], v[2:5]
	v_lshl_add_u64 v[6:7], v[48:49], 0, v[36:37]
	s_nop 6
	global_store_dwordx4 v[6:7], v[2:5], off
	v_lshl_add_u64 v[6:7], v[48:49], 0, v[78:79]
	s_nop 0
	v_mfma_f32_16x16x32_bf16 v[2:5], v[40:43], v[14:17], 0
	v_mfma_f32_16x16x32_bf16 v[2:5], v[44:47], v[26:29], v[2:5]
	s_nop 7
	global_store_dwordx4 v[6:7], v[2:5], off
	s_barrier
	s_cbranch_execz .LBB0_1108
	s_branch .LBB0_1799
.LBB0_1797:
	s_movk_i32 s30, 0x1ff
	s_or_b64 exec, exec, s[0:1]
	s_barrier
	s_mov_b64 s[0:1], -1
	s_and_b64 vcc, exec, s[68:69]
	s_cbranch_vccnz .LBB0_1244
